# rebalanced LDS-DMA staging 4/4/4/4 per load segment (was 2/6/2/6), counted waits vmcnt(8)/(6), in 5 big GEMM loops
# speedup vs baseline: 1.0143x; 1.0028x over previous
.LBB0_272:
	s_add_u32 s58, s22, 0xfff00000
	s_addc_u32 s59, s23, -1
	s_mov_b32 m0, s36
	ds_read_b128 v[154:157], v148
	global_load_lds_dwordx4 v130, s[58:59]
	s_mov_b32 m0, s37
	ds_read_b128 v[158:161], v148 offset:1024
	global_load_lds_dwordx4 v134, s[58:59]
	s_mov_b32 m0, s40
	ds_read_b128 v[164:167], v148 offset:2048
	global_load_lds_dwordx4 v142, s[22:23]
	s_mov_b32 m0, s41
	ds_read_b128 v[168:171], v148 offset:3072
	global_load_lds_dwordx4 v144, s[22:23]
	ds_read_b128 v[172:175], v149
	ds_read_b128 v[176:179], v149 offset:1024
	ds_read_b128 v[180:183], v149 offset:2048
	ds_read_b128 v[184:187], v149 offset:3072
	s_add_u32 s24, s22, 0xfff00080
	s_addc_u32 s25, s23, -1
	s_cmp_eq_u32 s56, 60
	s_cselect_b32 s27, s51, s25
	s_cselect_b32 s26, s52, s24
	s_cselect_b32 s25, s7, s55
	s_cselect_b32 s24, s53, s54
	ds_read_b128 v[188:191], v150
	ds_read_b128 v[192:195], v150 offset:1024
	ds_read_b128 v[196:199], v150 offset:2048
	ds_read_b128 v[200:203], v150 offset:3072
	ds_read_b128 v[204:207], v150 offset:4096
	ds_read_b128 v[208:211], v150 offset:5120
	ds_read_b128 v[212:215], v150 offset:6144
	ds_read_b128 v[216:219], v150 offset:7168
	s_waitcnt vmcnt(8)
	s_waitcnt lgkmcnt(0)
	s_barrier
	s_setprio 1
	s_waitcnt lgkmcnt(0)
	v_mfma_f32_16x16x32_bf16 v[126:129], v[154:157], v[188:191], v[126:129]
	v_mfma_f32_16x16x32_bf16 v[122:125], v[164:167], v[188:191], v[122:125]
	v_mfma_f32_16x16x32_bf16 v[118:121], v[154:157], v[196:199], v[118:121]
	v_mfma_f32_16x16x32_bf16 v[114:117], v[164:167], v[196:199], v[114:117]
	v_mfma_f32_16x16x32_bf16 v[102:105], v[154:157], v[204:207], v[102:105]
	v_mfma_f32_16x16x32_bf16 v[98:101], v[164:167], v[204:207], v[98:101]
	v_mfma_f32_16x16x32_bf16 v[86:89], v[154:157], v[212:215], v[86:89]
	v_mfma_f32_16x16x32_bf16 v[82:85], v[164:167], v[212:215], v[82:85]
	v_mfma_f32_16x16x32_bf16 v[126:129], v[158:161], v[192:195], v[126:129]
	v_mfma_f32_16x16x32_bf16 v[122:125], v[168:171], v[192:195], v[122:125]
	v_mfma_f32_16x16x32_bf16 v[118:121], v[158:161], v[200:203], v[118:121]
	v_mfma_f32_16x16x32_bf16 v[114:117], v[168:171], v[200:203], v[114:117]
	v_mfma_f32_16x16x32_bf16 v[102:105], v[158:161], v[208:211], v[102:105]
	v_mfma_f32_16x16x32_bf16 v[98:101], v[168:171], v[208:211], v[98:101]
	v_mfma_f32_16x16x32_bf16 v[86:89], v[158:161], v[216:219], v[86:89]
	v_mfma_f32_16x16x32_bf16 v[82:85], v[168:171], v[216:219], v[82:85]
	s_setprio 0
	s_setprio 1
	v_mfma_f32_16x16x32_bf16 v[110:113], v[172:175], v[188:191], v[110:113]
	v_mfma_f32_16x16x32_bf16 v[106:109], v[180:183], v[188:191], v[106:109]
	v_mfma_f32_16x16x32_bf16 v[94:97], v[172:175], v[196:199], v[94:97]
	v_mfma_f32_16x16x32_bf16 v[90:93], v[180:183], v[196:199], v[90:93]
	v_mfma_f32_16x16x32_bf16 v[78:81], v[172:175], v[204:207], v[78:81]
	v_mfma_f32_16x16x32_bf16 v[74:77], v[180:183], v[204:207], v[74:77]
	v_mfma_f32_16x16x32_bf16 v[70:73], v[172:175], v[212:215], v[70:73]
	v_mfma_f32_16x16x32_bf16 v[66:69], v[180:183], v[212:215], v[66:69]
	v_mfma_f32_16x16x32_bf16 v[110:113], v[176:179], v[192:195], v[110:113]
	v_mfma_f32_16x16x32_bf16 v[106:109], v[184:187], v[192:195], v[106:109]
	v_mfma_f32_16x16x32_bf16 v[94:97], v[176:179], v[200:203], v[94:97]
	v_mfma_f32_16x16x32_bf16 v[90:93], v[184:187], v[200:203], v[90:93]
	v_mfma_f32_16x16x32_bf16 v[78:81], v[176:179], v[208:211], v[78:81]
	v_mfma_f32_16x16x32_bf16 v[74:77], v[184:187], v[208:211], v[74:77]
	v_mfma_f32_16x16x32_bf16 v[70:73], v[176:179], v[216:219], v[70:73]
	v_mfma_f32_16x16x32_bf16 v[66:69], v[184:187], v[216:219], v[66:69]
	s_setprio 0
	s_barrier
	s_mov_b32 m0, s42
	s_add_u32 s58, s24, 0x100000
	global_load_lds_dwordx4 v132, s[24:25]
	s_mov_b32 m0, s43
	s_addc_u32 s59, s25, 0
	global_load_lds_dwordx4 v136, s[24:25]
	s_mov_b32 m0, s44
	ds_read_b128 v[188:191], v150 offset:16384
	global_load_lds_dwordx4 v132, s[58:59]
	s_mov_b32 m0, s45
	ds_read_b128 v[192:195], v150 offset:17408
	global_load_lds_dwordx4 v136, s[58:59]
	ds_read_b128 v[196:199], v150 offset:18432
	ds_read_b128 v[200:203], v150 offset:19456
	ds_read_b128 v[204:207], v150 offset:20480
	ds_read_b128 v[208:211], v150 offset:21504
	ds_read_b128 v[212:215], v150 offset:22528
	ds_read_b128 v[216:219], v150 offset:23552
	s_waitcnt vmcnt(6)
	s_waitcnt lgkmcnt(0)
	s_barrier
	s_setprio 1
	s_waitcnt lgkmcnt(0)
	v_mfma_f32_16x16x32_bf16 v[62:65], v[154:157], v[188:191], v[62:65]
	v_mfma_f32_16x16x32_bf16 v[58:61], v[164:167], v[188:191], v[58:61]
	v_mfma_f32_16x16x32_bf16 v[54:57], v[154:157], v[196:199], v[54:57]
	v_mfma_f32_16x16x32_bf16 v[50:53], v[164:167], v[196:199], v[50:53]
	v_mfma_f32_16x16x32_bf16 v[38:41], v[154:157], v[204:207], v[38:41]
	v_mfma_f32_16x16x32_bf16 v[34:37], v[164:167], v[204:207], v[34:37]
	v_mfma_f32_16x16x32_bf16 v[22:25], v[154:157], v[212:215], v[22:25]
	v_mfma_f32_16x16x32_bf16 v[18:21], v[164:167], v[212:215], v[18:21]
	v_mfma_f32_16x16x32_bf16 v[62:65], v[158:161], v[192:195], v[62:65]
	v_mfma_f32_16x16x32_bf16 v[58:61], v[168:171], v[192:195], v[58:61]
	v_mfma_f32_16x16x32_bf16 v[54:57], v[158:161], v[200:203], v[54:57]
	v_mfma_f32_16x16x32_bf16 v[50:53], v[168:171], v[200:203], v[50:53]
	v_mfma_f32_16x16x32_bf16 v[38:41], v[158:161], v[208:211], v[38:41]
	v_mfma_f32_16x16x32_bf16 v[34:37], v[168:171], v[208:211], v[34:37]
	v_mfma_f32_16x16x32_bf16 v[22:25], v[158:161], v[216:219], v[22:25]
	v_mfma_f32_16x16x32_bf16 v[18:21], v[168:171], v[216:219], v[18:21]
	s_setprio 0
	s_setprio 1
	v_mfma_f32_16x16x32_bf16 v[46:49], v[172:175], v[188:191], v[46:49]
	v_mfma_f32_16x16x32_bf16 v[42:45], v[180:183], v[188:191], v[42:45]
	v_mfma_f32_16x16x32_bf16 v[30:33], v[172:175], v[196:199], v[30:33]
	v_mfma_f32_16x16x32_bf16 v[26:29], v[180:183], v[196:199], v[26:29]
	v_mfma_f32_16x16x32_bf16 v[14:17], v[172:175], v[204:207], v[14:17]
	v_mfma_f32_16x16x32_bf16 v[10:13], v[180:183], v[204:207], v[10:13]
	v_mfma_f32_16x16x32_bf16 v[6:9], v[172:175], v[212:215], v[6:9]
	v_mfma_f32_16x16x32_bf16 v[2:5], v[180:183], v[212:215], v[2:5]
	v_mfma_f32_16x16x32_bf16 v[46:49], v[176:179], v[192:195], v[46:49]
	v_mfma_f32_16x16x32_bf16 v[42:45], v[184:187], v[192:195], v[42:45]
	v_mfma_f32_16x16x32_bf16 v[30:33], v[176:179], v[200:203], v[30:33]
	v_mfma_f32_16x16x32_bf16 v[26:29], v[184:187], v[200:203], v[26:29]
	v_mfma_f32_16x16x32_bf16 v[14:17], v[176:179], v[208:211], v[14:17]
	v_mfma_f32_16x16x32_bf16 v[10:13], v[184:187], v[208:211], v[10:13]
	v_mfma_f32_16x16x32_bf16 v[6:9], v[176:179], v[216:219], v[6:9]
	v_mfma_f32_16x16x32_bf16 v[2:5], v[184:187], v[216:219], v[2:5]
	s_setprio 0
	s_barrier
	s_mov_b32 m0, s30
	ds_read_b128 v[154:157], v151
	global_load_lds_dwordx4 v130, s[26:27]
	s_mov_b32 m0, s31
	ds_read_b128 v[158:161], v151 offset:1024
	global_load_lds_dwordx4 v134, s[26:27]
	s_add_u32 s26, s26, 0x100000
	s_addc_u32 s27, s27, 0
	s_mov_b32 m0, s33
	ds_read_b128 v[164:167], v151 offset:2048
	global_load_lds_dwordx4 v130, s[26:27]
	s_mov_b32 m0, s34
	ds_read_b128 v[168:171], v151 offset:3072
	global_load_lds_dwordx4 v134, s[26:27]
	ds_read_b128 v[172:175], v152
	ds_read_b128 v[176:179], v152 offset:1024
	ds_read_b128 v[180:183], v152 offset:2048
	ds_read_b128 v[184:187], v152 offset:3072
	ds_read_b128 v[188:191], v150 offset:32768
	ds_read_b128 v[192:195], v150 offset:33792
	ds_read_b128 v[196:199], v150 offset:34816
	ds_read_b128 v[200:203], v150 offset:35840
	ds_read_b128 v[204:207], v150 offset:36864
	ds_read_b128 v[208:211], v150 offset:37888
	ds_read_b128 v[212:215], v150 offset:38912
	ds_read_b128 v[216:219], v150 offset:39936
	s_waitcnt vmcnt(8)
	s_waitcnt lgkmcnt(0)
	s_barrier
	s_setprio 1
	s_waitcnt lgkmcnt(0)
	v_mfma_f32_16x16x32_bf16 v[126:129], v[154:157], v[188:191], v[126:129]
	v_mfma_f32_16x16x32_bf16 v[122:125], v[164:167], v[188:191], v[122:125]
	v_mfma_f32_16x16x32_bf16 v[118:121], v[154:157], v[196:199], v[118:121]
	v_mfma_f32_16x16x32_bf16 v[114:117], v[164:167], v[196:199], v[114:117]
	v_mfma_f32_16x16x32_bf16 v[102:105], v[154:157], v[204:207], v[102:105]
	v_mfma_f32_16x16x32_bf16 v[98:101], v[164:167], v[204:207], v[98:101]
	v_mfma_f32_16x16x32_bf16 v[86:89], v[154:157], v[212:215], v[86:89]
	v_mfma_f32_16x16x32_bf16 v[82:85], v[164:167], v[212:215], v[82:85]
	v_mfma_f32_16x16x32_bf16 v[126:129], v[158:161], v[192:195], v[126:129]
	v_mfma_f32_16x16x32_bf16 v[122:125], v[168:171], v[192:195], v[122:125]
	v_mfma_f32_16x16x32_bf16 v[118:121], v[158:161], v[200:203], v[118:121]
	v_mfma_f32_16x16x32_bf16 v[114:117], v[168:171], v[200:203], v[114:117]
	v_mfma_f32_16x16x32_bf16 v[102:105], v[158:161], v[208:211], v[102:105]
	v_mfma_f32_16x16x32_bf16 v[98:101], v[168:171], v[208:211], v[98:101]
	v_mfma_f32_16x16x32_bf16 v[86:89], v[158:161], v[216:219], v[86:89]
	v_mfma_f32_16x16x32_bf16 v[82:85], v[168:171], v[216:219], v[82:85]
	s_setprio 0
	s_setprio 1
	v_mfma_f32_16x16x32_bf16 v[110:113], v[172:175], v[188:191], v[110:113]
	v_mfma_f32_16x16x32_bf16 v[106:109], v[180:183], v[188:191], v[106:109]
	v_mfma_f32_16x16x32_bf16 v[94:97], v[172:175], v[196:199], v[94:97]
	v_mfma_f32_16x16x32_bf16 v[90:93], v[180:183], v[196:199], v[90:93]
	v_mfma_f32_16x16x32_bf16 v[78:81], v[172:175], v[204:207], v[78:81]
	v_mfma_f32_16x16x32_bf16 v[74:77], v[180:183], v[204:207], v[74:77]
	v_mfma_f32_16x16x32_bf16 v[70:73], v[172:175], v[212:215], v[70:73]
	v_mfma_f32_16x16x32_bf16 v[66:69], v[180:183], v[212:215], v[66:69]
	v_mfma_f32_16x16x32_bf16 v[110:113], v[176:179], v[192:195], v[110:113]
	v_mfma_f32_16x16x32_bf16 v[106:109], v[184:187], v[192:195], v[106:109]
	v_mfma_f32_16x16x32_bf16 v[94:97], v[176:179], v[200:203], v[94:97]
	v_mfma_f32_16x16x32_bf16 v[90:93], v[184:187], v[200:203], v[90:93]
	v_mfma_f32_16x16x32_bf16 v[78:81], v[176:179], v[208:211], v[78:81]
	v_mfma_f32_16x16x32_bf16 v[74:77], v[184:187], v[208:211], v[74:77]
	v_mfma_f32_16x16x32_bf16 v[70:73], v[176:179], v[216:219], v[70:73]
	v_mfma_f32_16x16x32_bf16 v[66:69], v[184:187], v[216:219], v[66:69]
	s_setprio 0
	s_barrier
	s_mov_b32 m0, s47
	s_add_u32 s24, s24, 0x80
	s_addc_u32 s25, s25, 0
	global_load_lds_dwordx4 v132, s[24:25]
	s_mov_b32 m0, s48
	ds_read_b128 v[188:191], v150 offset:49152
	global_load_lds_dwordx4 v136, s[24:25]
	s_add_i32 s26, s46, s29
	s_mov_b32 m0, s26
	s_add_u32 s24, s24, 0x100000
	s_addc_u32 s25, s25, 0
	global_load_lds_dwordx4 v132, s[24:25]
	s_add_i32 m0, s26, 0x2000
	ds_read_b128 v[192:195], v150 offset:50176
	global_load_lds_dwordx4 v136, s[24:25]
	ds_read_b128 v[196:199], v150 offset:51200
	ds_read_b128 v[200:203], v150 offset:52224
	ds_read_b128 v[204:207], v150 offset:53248
	ds_read_b128 v[208:211], v150 offset:54272
	ds_read_b128 v[212:215], v150 offset:55296
	ds_read_b128 v[216:219], v150 offset:56320
	s_waitcnt vmcnt(6)
	s_waitcnt lgkmcnt(0)
	s_barrier
	s_setprio 1
	s_waitcnt lgkmcnt(0)
	v_mfma_f32_16x16x32_bf16 v[62:65], v[154:157], v[188:191], v[62:65]
	v_mfma_f32_16x16x32_bf16 v[58:61], v[164:167], v[188:191], v[58:61]
	v_mfma_f32_16x16x32_bf16 v[54:57], v[154:157], v[196:199], v[54:57]
	v_mfma_f32_16x16x32_bf16 v[50:53], v[164:167], v[196:199], v[50:53]
	v_mfma_f32_16x16x32_bf16 v[38:41], v[154:157], v[204:207], v[38:41]
	v_mfma_f32_16x16x32_bf16 v[34:37], v[164:167], v[204:207], v[34:37]
	v_mfma_f32_16x16x32_bf16 v[22:25], v[154:157], v[212:215], v[22:25]
	v_mfma_f32_16x16x32_bf16 v[18:21], v[164:167], v[212:215], v[18:21]
	v_mfma_f32_16x16x32_bf16 v[62:65], v[158:161], v[192:195], v[62:65]
	v_mfma_f32_16x16x32_bf16 v[58:61], v[168:171], v[192:195], v[58:61]
	v_mfma_f32_16x16x32_bf16 v[54:57], v[158:161], v[200:203], v[54:57]
	v_mfma_f32_16x16x32_bf16 v[50:53], v[168:171], v[200:203], v[50:53]
	v_mfma_f32_16x16x32_bf16 v[38:41], v[158:161], v[208:211], v[38:41]
	v_mfma_f32_16x16x32_bf16 v[34:37], v[168:171], v[208:211], v[34:37]
	v_mfma_f32_16x16x32_bf16 v[22:25], v[158:161], v[216:219], v[22:25]
	v_mfma_f32_16x16x32_bf16 v[18:21], v[168:171], v[216:219], v[18:21]
	s_setprio 0
	s_setprio 1
	v_mfma_f32_16x16x32_bf16 v[46:49], v[172:175], v[188:191], v[46:49]
	v_mfma_f32_16x16x32_bf16 v[42:45], v[180:183], v[188:191], v[42:45]
	v_mfma_f32_16x16x32_bf16 v[30:33], v[172:175], v[196:199], v[30:33]
	v_mfma_f32_16x16x32_bf16 v[26:29], v[180:183], v[196:199], v[26:29]
	v_mfma_f32_16x16x32_bf16 v[14:17], v[172:175], v[204:207], v[14:17]
	v_mfma_f32_16x16x32_bf16 v[10:13], v[180:183], v[204:207], v[10:13]
	v_mfma_f32_16x16x32_bf16 v[6:9], v[172:175], v[212:215], v[6:9]
	v_mfma_f32_16x16x32_bf16 v[2:5], v[180:183], v[212:215], v[2:5]
	v_mfma_f32_16x16x32_bf16 v[46:49], v[176:179], v[192:195], v[46:49]
	v_mfma_f32_16x16x32_bf16 v[42:45], v[184:187], v[192:195], v[42:45]
	v_mfma_f32_16x16x32_bf16 v[30:33], v[176:179], v[200:203], v[30:33]
	v_mfma_f32_16x16x32_bf16 v[26:29], v[184:187], v[200:203], v[26:29]
	v_mfma_f32_16x16x32_bf16 v[14:17], v[176:179], v[208:211], v[14:17]
	v_mfma_f32_16x16x32_bf16 v[10:13], v[184:187], v[208:211], v[10:13]
	v_mfma_f32_16x16x32_bf16 v[6:9], v[176:179], v[216:219], v[6:9]
	v_mfma_f32_16x16x32_bf16 v[2:5], v[184:187], v[216:219], v[2:5]
	s_setprio 0
	s_barrier
	s_add_i32 s56, s56, 2
	s_add_u32 s22, s22, 0x100
	s_addc_u32 s23, s23, 0
	s_add_u32 s54, s54, 0x100
	s_addc_u32 s55, s55, 0
	s_cmp_gt_u32 s56, 61
	s_cbranch_scc0 .LBB0_272
	s_and_b64 vcc, exec, s[16:17]
	s_cbranch_vccz .LBB0_277
	s_barrier
	v_lshl_add_u32 v138, s50, 8, v1
	s_cmp_gt_i32 s49, 63
	s_mov_b64 s[22:23], -1
	s_cbranch_scc1 .LBB0_278

.LBB0_1172:
	s_add_u32 s62, s20, 0xfff00000
	s_addc_u32 s63, s21, -1
	s_mov_b32 m0, s37
	ds_read_b128 v[142:145], v148
	global_load_lds_dwordx4 v130, s[62:63]
	s_mov_b32 m0, s38
	ds_read_b128 v[154:157], v148 offset:1024
	global_load_lds_dwordx4 v134, s[62:63]
	s_mov_b32 m0, s42
	ds_read_b128 v[158:161], v148 offset:2048
	global_load_lds_dwordx4 v138, s[20:21]
	s_mov_b32 m0, s43
	ds_read_b128 v[168:171], v148 offset:3072
	global_load_lds_dwordx4 v140, s[20:21]
	ds_read_b128 v[176:179], v149
	ds_read_b128 v[180:183], v149 offset:1024
	ds_read_b128 v[184:187], v149 offset:2048
	ds_read_b128 v[188:191], v149 offset:3072
	s_add_u32 s22, s20, 0xfff00080
	s_addc_u32 s23, s21, -1
	s_cmp_eq_u32 s61, 60
	s_cselect_b32 s25, s54, s23
	s_cselect_b32 s24, s55, s22
	s_cselect_b32 s23, s7, s60
	s_cselect_b32 s22, s56, s57
	ds_read_b128 v[192:195], v150
	ds_read_b128 v[202:205], v150 offset:1024
	ds_read_b128 v[206:209], v150 offset:2048
	ds_read_b128 v[210:213], v150 offset:3072
	ds_read_b128 v[214:217], v150 offset:4096
	ds_read_b128 v[218:221], v150 offset:5120
	ds_read_b128 v[222:225], v150 offset:6144
	ds_read_b128 v[226:229], v150 offset:7168
	s_waitcnt vmcnt(8)
	s_waitcnt lgkmcnt(0)
	s_barrier
	s_setprio 1
	s_waitcnt lgkmcnt(0)
	v_mfma_f32_16x16x32_bf16 v[126:129], v[142:145], v[192:195], v[126:129]
	v_mfma_f32_16x16x32_bf16 v[118:121], v[158:161], v[192:195], v[118:121]
	v_mfma_f32_16x16x32_bf16 v[110:113], v[142:145], v[206:209], v[110:113]
	v_mfma_f32_16x16x32_bf16 v[102:105], v[158:161], v[206:209], v[102:105]
	v_mfma_f32_16x16x32_bf16 v[94:97], v[142:145], v[214:217], v[94:97]
	v_mfma_f32_16x16x32_bf16 v[86:89], v[158:161], v[214:217], v[86:89]
	v_mfma_f32_16x16x32_bf16 v[78:81], v[142:145], v[222:225], v[78:81]
	v_mfma_f32_16x16x32_bf16 v[70:73], v[158:161], v[222:225], v[70:73]
	v_mfma_f32_16x16x32_bf16 v[126:129], v[154:157], v[202:205], v[126:129]
	v_mfma_f32_16x16x32_bf16 v[118:121], v[168:171], v[202:205], v[118:121]
	v_mfma_f32_16x16x32_bf16 v[110:113], v[154:157], v[210:213], v[110:113]
	v_mfma_f32_16x16x32_bf16 v[102:105], v[168:171], v[210:213], v[102:105]
	v_mfma_f32_16x16x32_bf16 v[94:97], v[154:157], v[218:221], v[94:97]
	v_mfma_f32_16x16x32_bf16 v[86:89], v[168:171], v[218:221], v[86:89]
	v_mfma_f32_16x16x32_bf16 v[78:81], v[154:157], v[226:229], v[78:81]
	v_mfma_f32_16x16x32_bf16 v[70:73], v[168:171], v[226:229], v[70:73]
	s_setprio 0
	s_setprio 1
	v_mfma_f32_16x16x32_bf16 v[122:125], v[176:179], v[192:195], v[122:125]
	v_mfma_f32_16x16x32_bf16 v[114:117], v[184:187], v[192:195], v[114:117]
	v_mfma_f32_16x16x32_bf16 v[106:109], v[176:179], v[206:209], v[106:109]
	v_mfma_f32_16x16x32_bf16 v[98:101], v[184:187], v[206:209], v[98:101]
	v_mfma_f32_16x16x32_bf16 v[90:93], v[176:179], v[214:217], v[90:93]
	v_mfma_f32_16x16x32_bf16 v[82:85], v[184:187], v[214:217], v[82:85]
	v_mfma_f32_16x16x32_bf16 v[74:77], v[176:179], v[222:225], v[74:77]
	v_mfma_f32_16x16x32_bf16 v[66:69], v[184:187], v[222:225], v[66:69]
	v_mfma_f32_16x16x32_bf16 v[122:125], v[180:183], v[202:205], v[122:125]
	v_mfma_f32_16x16x32_bf16 v[114:117], v[188:191], v[202:205], v[114:117]
	v_mfma_f32_16x16x32_bf16 v[106:109], v[180:183], v[210:213], v[106:109]
	v_mfma_f32_16x16x32_bf16 v[98:101], v[188:191], v[210:213], v[98:101]
	v_mfma_f32_16x16x32_bf16 v[90:93], v[180:183], v[218:221], v[90:93]
	v_mfma_f32_16x16x32_bf16 v[82:85], v[188:191], v[218:221], v[82:85]
	v_mfma_f32_16x16x32_bf16 v[74:77], v[180:183], v[226:229], v[74:77]
	v_mfma_f32_16x16x32_bf16 v[66:69], v[188:191], v[226:229], v[66:69]
	s_setprio 0
	s_barrier
	s_mov_b32 m0, s44
	s_add_u32 s62, s22, 0x100000
	global_load_lds_dwordx4 v132, s[22:23]
	s_mov_b32 m0, s45
	s_addc_u32 s63, s23, 0
	global_load_lds_dwordx4 v136, s[22:23]
	s_mov_b32 m0, s46
	ds_read_b128 v[192:195], v150 offset:16384
	global_load_lds_dwordx4 v132, s[62:63]
	s_mov_b32 m0, s47
	ds_read_b128 v[202:205], v150 offset:17408
	global_load_lds_dwordx4 v136, s[62:63]
	ds_read_b128 v[206:209], v150 offset:18432
	ds_read_b128 v[210:213], v150 offset:19456
	ds_read_b128 v[214:217], v150 offset:20480
	ds_read_b128 v[218:221], v150 offset:21504
	ds_read_b128 v[222:225], v150 offset:22528
	ds_read_b128 v[226:229], v150 offset:23552
	s_waitcnt vmcnt(6)
	s_waitcnt lgkmcnt(0)
	s_barrier
	s_setprio 1
	s_waitcnt lgkmcnt(0)
	v_mfma_f32_16x16x32_bf16 v[62:65], v[142:145], v[192:195], v[62:65]
	v_mfma_f32_16x16x32_bf16 v[54:57], v[158:161], v[192:195], v[54:57]
	v_mfma_f32_16x16x32_bf16 v[46:49], v[142:145], v[206:209], v[46:49]
	v_mfma_f32_16x16x32_bf16 v[38:41], v[158:161], v[206:209], v[38:41]
	v_mfma_f32_16x16x32_bf16 v[30:33], v[142:145], v[214:217], v[30:33]
	v_mfma_f32_16x16x32_bf16 v[22:25], v[158:161], v[214:217], v[22:25]
	v_mfma_f32_16x16x32_bf16 v[14:17], v[142:145], v[222:225], v[14:17]
	v_mfma_f32_16x16x32_bf16 v[6:9], v[158:161], v[222:225], v[6:9]
	v_mfma_f32_16x16x32_bf16 v[62:65], v[154:157], v[202:205], v[62:65]
	v_mfma_f32_16x16x32_bf16 v[54:57], v[168:171], v[202:205], v[54:57]
	v_mfma_f32_16x16x32_bf16 v[46:49], v[154:157], v[210:213], v[46:49]
	v_mfma_f32_16x16x32_bf16 v[38:41], v[168:171], v[210:213], v[38:41]
	v_mfma_f32_16x16x32_bf16 v[30:33], v[154:157], v[218:221], v[30:33]
	v_mfma_f32_16x16x32_bf16 v[22:25], v[168:171], v[218:221], v[22:25]
	v_mfma_f32_16x16x32_bf16 v[14:17], v[154:157], v[226:229], v[14:17]
	v_mfma_f32_16x16x32_bf16 v[6:9], v[168:171], v[226:229], v[6:9]
	s_setprio 0
	s_setprio 1
	v_mfma_f32_16x16x32_bf16 v[58:61], v[176:179], v[192:195], v[58:61]
	v_mfma_f32_16x16x32_bf16 v[50:53], v[184:187], v[192:195], v[50:53]
	v_mfma_f32_16x16x32_bf16 v[42:45], v[176:179], v[206:209], v[42:45]
	v_mfma_f32_16x16x32_bf16 v[34:37], v[184:187], v[206:209], v[34:37]
	v_mfma_f32_16x16x32_bf16 v[26:29], v[176:179], v[214:217], v[26:29]
	v_mfma_f32_16x16x32_bf16 v[18:21], v[184:187], v[214:217], v[18:21]
	v_mfma_f32_16x16x32_bf16 v[10:13], v[176:179], v[222:225], v[10:13]
	v_mfma_f32_16x16x32_bf16 v[2:5], v[184:187], v[222:225], v[2:5]
	v_mfma_f32_16x16x32_bf16 v[58:61], v[180:183], v[202:205], v[58:61]
	v_mfma_f32_16x16x32_bf16 v[50:53], v[188:191], v[202:205], v[50:53]
	v_mfma_f32_16x16x32_bf16 v[42:45], v[180:183], v[210:213], v[42:45]
	v_mfma_f32_16x16x32_bf16 v[34:37], v[188:191], v[210:213], v[34:37]
	v_mfma_f32_16x16x32_bf16 v[26:29], v[180:183], v[218:221], v[26:29]
	v_mfma_f32_16x16x32_bf16 v[18:21], v[188:191], v[218:221], v[18:21]
	v_mfma_f32_16x16x32_bf16 v[10:13], v[180:183], v[226:229], v[10:13]
	v_mfma_f32_16x16x32_bf16 v[2:5], v[188:191], v[226:229], v[2:5]
	s_setprio 0
	s_barrier
	s_mov_b32 m0, s31
	ds_read_b128 v[142:145], v151
	global_load_lds_dwordx4 v130, s[24:25]
	s_mov_b32 m0, s33
	ds_read_b128 v[154:157], v151 offset:1024
	global_load_lds_dwordx4 v134, s[24:25]
	s_add_u32 s24, s24, 0x100000
	s_addc_u32 s25, s25, 0
	s_mov_b32 m0, s34
	ds_read_b128 v[158:161], v151 offset:2048
	global_load_lds_dwordx4 v130, s[24:25]
	s_mov_b32 m0, s35
	ds_read_b128 v[168:171], v151 offset:3072
	global_load_lds_dwordx4 v134, s[24:25]
	ds_read_b128 v[176:179], v152
	ds_read_b128 v[180:183], v152 offset:1024
	ds_read_b128 v[184:187], v152 offset:2048
	ds_read_b128 v[188:191], v152 offset:3072
	ds_read_b128 v[192:195], v150 offset:32768
	ds_read_b128 v[202:205], v150 offset:33792
	ds_read_b128 v[206:209], v150 offset:34816
	ds_read_b128 v[210:213], v150 offset:35840
	ds_read_b128 v[214:217], v150 offset:36864
	ds_read_b128 v[218:221], v150 offset:37888
	ds_read_b128 v[222:225], v150 offset:38912
	ds_read_b128 v[226:229], v150 offset:39936
	s_waitcnt vmcnt(8)
	s_waitcnt lgkmcnt(0)
	s_barrier
	s_setprio 1
	s_waitcnt lgkmcnt(0)
	v_mfma_f32_16x16x32_bf16 v[126:129], v[142:145], v[192:195], v[126:129]
	v_mfma_f32_16x16x32_bf16 v[118:121], v[158:161], v[192:195], v[118:121]
	v_mfma_f32_16x16x32_bf16 v[110:113], v[142:145], v[206:209], v[110:113]
	v_mfma_f32_16x16x32_bf16 v[102:105], v[158:161], v[206:209], v[102:105]
	v_mfma_f32_16x16x32_bf16 v[94:97], v[142:145], v[214:217], v[94:97]
	v_mfma_f32_16x16x32_bf16 v[86:89], v[158:161], v[214:217], v[86:89]
	v_mfma_f32_16x16x32_bf16 v[78:81], v[142:145], v[222:225], v[78:81]
	v_mfma_f32_16x16x32_bf16 v[70:73], v[158:161], v[222:225], v[70:73]
	v_mfma_f32_16x16x32_bf16 v[126:129], v[154:157], v[202:205], v[126:129]
	v_mfma_f32_16x16x32_bf16 v[118:121], v[168:171], v[202:205], v[118:121]
	v_mfma_f32_16x16x32_bf16 v[110:113], v[154:157], v[210:213], v[110:113]
	v_mfma_f32_16x16x32_bf16 v[102:105], v[168:171], v[210:213], v[102:105]
	v_mfma_f32_16x16x32_bf16 v[94:97], v[154:157], v[218:221], v[94:97]
	v_mfma_f32_16x16x32_bf16 v[86:89], v[168:171], v[218:221], v[86:89]
	v_mfma_f32_16x16x32_bf16 v[78:81], v[154:157], v[226:229], v[78:81]
	v_mfma_f32_16x16x32_bf16 v[70:73], v[168:171], v[226:229], v[70:73]
	s_setprio 0
	s_setprio 1
	v_mfma_f32_16x16x32_bf16 v[122:125], v[176:179], v[192:195], v[122:125]
	v_mfma_f32_16x16x32_bf16 v[114:117], v[184:187], v[192:195], v[114:117]
	v_mfma_f32_16x16x32_bf16 v[106:109], v[176:179], v[206:209], v[106:109]
	v_mfma_f32_16x16x32_bf16 v[98:101], v[184:187], v[206:209], v[98:101]
	v_mfma_f32_16x16x32_bf16 v[90:93], v[176:179], v[214:217], v[90:93]
	v_mfma_f32_16x16x32_bf16 v[82:85], v[184:187], v[214:217], v[82:85]
	v_mfma_f32_16x16x32_bf16 v[74:77], v[176:179], v[222:225], v[74:77]
	v_mfma_f32_16x16x32_bf16 v[66:69], v[184:187], v[222:225], v[66:69]
	v_mfma_f32_16x16x32_bf16 v[122:125], v[180:183], v[202:205], v[122:125]
	v_mfma_f32_16x16x32_bf16 v[114:117], v[188:191], v[202:205], v[114:117]
	v_mfma_f32_16x16x32_bf16 v[106:109], v[180:183], v[210:213], v[106:109]
	v_mfma_f32_16x16x32_bf16 v[98:101], v[188:191], v[210:213], v[98:101]
	v_mfma_f32_16x16x32_bf16 v[90:93], v[180:183], v[218:221], v[90:93]
	v_mfma_f32_16x16x32_bf16 v[82:85], v[188:191], v[218:221], v[82:85]
	v_mfma_f32_16x16x32_bf16 v[74:77], v[180:183], v[226:229], v[74:77]
	v_mfma_f32_16x16x32_bf16 v[66:69], v[188:191], v[226:229], v[66:69]
	s_setprio 0
	s_barrier
	s_mov_b32 m0, s48
	s_add_u32 s22, s22, 0x80
	s_addc_u32 s23, s23, 0
	global_load_lds_dwordx4 v132, s[22:23]
	s_mov_b32 m0, s49
	ds_read_b128 v[192:195], v150 offset:49152
	global_load_lds_dwordx4 v136, s[22:23]
	s_mov_b32 m0, s50
	s_add_u32 s22, s22, 0x100000
	s_addc_u32 s23, s23, 0
	global_load_lds_dwordx4 v132, s[22:23]
	s_mov_b32 m0, s51
	ds_read_b128 v[202:205], v150 offset:50176
	global_load_lds_dwordx4 v136, s[22:23]
	ds_read_b128 v[206:209], v150 offset:51200
	ds_read_b128 v[210:213], v150 offset:52224
	ds_read_b128 v[214:217], v150 offset:53248
	ds_read_b128 v[218:221], v150 offset:54272
	ds_read_b128 v[222:225], v150 offset:55296
	ds_read_b128 v[226:229], v150 offset:56320
	s_waitcnt vmcnt(6)
	s_waitcnt lgkmcnt(0)
	s_barrier
	s_setprio 1
	s_waitcnt lgkmcnt(0)
	v_mfma_f32_16x16x32_bf16 v[62:65], v[142:145], v[192:195], v[62:65]
	v_mfma_f32_16x16x32_bf16 v[54:57], v[158:161], v[192:195], v[54:57]
	v_mfma_f32_16x16x32_bf16 v[46:49], v[142:145], v[206:209], v[46:49]
	v_mfma_f32_16x16x32_bf16 v[38:41], v[158:161], v[206:209], v[38:41]
	v_mfma_f32_16x16x32_bf16 v[30:33], v[142:145], v[214:217], v[30:33]
	v_mfma_f32_16x16x32_bf16 v[22:25], v[158:161], v[214:217], v[22:25]
	v_mfma_f32_16x16x32_bf16 v[14:17], v[142:145], v[222:225], v[14:17]
	v_mfma_f32_16x16x32_bf16 v[6:9], v[158:161], v[222:225], v[6:9]
	v_mfma_f32_16x16x32_bf16 v[62:65], v[154:157], v[202:205], v[62:65]
	v_mfma_f32_16x16x32_bf16 v[54:57], v[168:171], v[202:205], v[54:57]
	v_mfma_f32_16x16x32_bf16 v[46:49], v[154:157], v[210:213], v[46:49]
	v_mfma_f32_16x16x32_bf16 v[38:41], v[168:171], v[210:213], v[38:41]
	v_mfma_f32_16x16x32_bf16 v[30:33], v[154:157], v[218:221], v[30:33]
	v_mfma_f32_16x16x32_bf16 v[22:25], v[168:171], v[218:221], v[22:25]
	v_mfma_f32_16x16x32_bf16 v[14:17], v[154:157], v[226:229], v[14:17]
	v_mfma_f32_16x16x32_bf16 v[6:9], v[168:171], v[226:229], v[6:9]
	s_setprio 0
	s_setprio 1
	v_mfma_f32_16x16x32_bf16 v[58:61], v[176:179], v[192:195], v[58:61]
	v_mfma_f32_16x16x32_bf16 v[50:53], v[184:187], v[192:195], v[50:53]
	v_mfma_f32_16x16x32_bf16 v[42:45], v[176:179], v[206:209], v[42:45]
	v_mfma_f32_16x16x32_bf16 v[34:37], v[184:187], v[206:209], v[34:37]
	v_mfma_f32_16x16x32_bf16 v[26:29], v[176:179], v[214:217], v[26:29]
	v_mfma_f32_16x16x32_bf16 v[18:21], v[184:187], v[214:217], v[18:21]
	v_mfma_f32_16x16x32_bf16 v[10:13], v[176:179], v[222:225], v[10:13]
	v_mfma_f32_16x16x32_bf16 v[2:5], v[184:187], v[222:225], v[2:5]
	v_mfma_f32_16x16x32_bf16 v[58:61], v[180:183], v[202:205], v[58:61]
	v_mfma_f32_16x16x32_bf16 v[50:53], v[188:191], v[202:205], v[50:53]
	v_mfma_f32_16x16x32_bf16 v[42:45], v[180:183], v[210:213], v[42:45]
	v_mfma_f32_16x16x32_bf16 v[34:37], v[188:191], v[210:213], v[34:37]
	v_mfma_f32_16x16x32_bf16 v[26:29], v[180:183], v[218:221], v[26:29]
	v_mfma_f32_16x16x32_bf16 v[18:21], v[188:191], v[218:221], v[18:21]
	v_mfma_f32_16x16x32_bf16 v[10:13], v[180:183], v[226:229], v[10:13]
	v_mfma_f32_16x16x32_bf16 v[2:5], v[188:191], v[226:229], v[2:5]
	s_setprio 0
	s_barrier
	s_add_i32 s61, s61, 2
	s_add_u32 s20, s20, 0x100
	s_addc_u32 s21, s21, 0
	s_add_u32 s57, s57, 0x100
	s_addc_u32 s60, s60, 0
	s_cmp_gt_u32 s61, 61
	s_cbranch_scc0 .LBB0_1172
	s_and_b64 vcc, exec, s[16:17]
	s_cbranch_vccz .LBB0_1175
	s_barrier

.LBB0_1418:
	s_add_u32 s56, s22, 0xffd50000
	s_addc_u32 s57, s23, -1
	s_mov_b32 m0, s40
	ds_read_b128 v[142:145], v156
	global_load_lds_dwordx4 v130, s[56:57]
	s_mov_b32 m0, s41
	ds_read_b128 v[168:171], v156 offset:1024
	global_load_lds_dwordx4 v134, s[56:57]
	s_mov_b32 m0, s42
	ds_read_b128 v[176:179], v156 offset:2048
	global_load_lds_dwordx4 v138, s[22:23]
	s_mov_b32 m0, s43
	ds_read_b128 v[180:183], v156 offset:3072
	global_load_lds_dwordx4 v140, s[22:23]
	ds_read_b128 v[184:187], v157
	ds_read_b128 v[188:191], v157 offset:1024
	ds_read_b128 v[192:195], v157 offset:2048
	ds_read_b128 v[204:207], v157 offset:3072
	s_add_u32 s24, s22, 0xffd50080
	s_addc_u32 s25, s23, -1
	s_cmpk_eq_i32 s55, 0xa8
	s_cselect_b32 s27, s19, s25
	s_cselect_b32 s26, s18, s24
	s_cselect_b32 s25, s17, s54
	s_cselect_b32 s24, s16, s53
	ds_read_b128 v[208:211], v158
	ds_read_b128 v[212:215], v158 offset:1024
	ds_read_b128 v[216:219], v158 offset:2048
	ds_read_b128 v[220:223], v158 offset:3072
	ds_read_b128 v[224:227], v158 offset:4096
	ds_read_b128 v[228:231], v158 offset:5120
	ds_read_b128 v[232:235], v158 offset:6144
	ds_read_b128 v[236:239], v158 offset:7168
	s_waitcnt vmcnt(8)
	s_waitcnt lgkmcnt(0)
	s_barrier
	s_setprio 1
	s_waitcnt lgkmcnt(0)
	v_mfma_f32_16x16x32_bf16 v[126:129], v[142:145], v[208:211], v[126:129]
	v_mfma_f32_16x16x32_bf16 v[122:125], v[176:179], v[208:211], v[122:125]
	v_mfma_f32_16x16x32_bf16 v[110:113], v[142:145], v[216:219], v[110:113]
	v_mfma_f32_16x16x32_bf16 v[106:109], v[176:179], v[216:219], v[106:109]
	v_mfma_f32_16x16x32_bf16 v[94:97], v[142:145], v[224:227], v[94:97]
	v_mfma_f32_16x16x32_bf16 v[90:93], v[176:179], v[224:227], v[90:93]
	v_mfma_f32_16x16x32_bf16 v[78:81], v[142:145], v[232:235], v[78:81]
	v_mfma_f32_16x16x32_bf16 v[74:77], v[176:179], v[232:235], v[74:77]
	v_mfma_f32_16x16x32_bf16 v[126:129], v[168:171], v[212:215], v[126:129]
	v_mfma_f32_16x16x32_bf16 v[122:125], v[180:183], v[212:215], v[122:125]
	v_mfma_f32_16x16x32_bf16 v[110:113], v[168:171], v[220:223], v[110:113]
	v_mfma_f32_16x16x32_bf16 v[106:109], v[180:183], v[220:223], v[106:109]
	v_mfma_f32_16x16x32_bf16 v[94:97], v[168:171], v[228:231], v[94:97]
	v_mfma_f32_16x16x32_bf16 v[90:93], v[180:183], v[228:231], v[90:93]
	v_mfma_f32_16x16x32_bf16 v[78:81], v[168:171], v[236:239], v[78:81]
	v_mfma_f32_16x16x32_bf16 v[74:77], v[180:183], v[236:239], v[74:77]
	s_setprio 0
	s_setprio 1
	v_mfma_f32_16x16x32_bf16 v[118:121], v[184:187], v[208:211], v[118:121]
	v_mfma_f32_16x16x32_bf16 v[114:117], v[192:195], v[208:211], v[114:117]
	v_mfma_f32_16x16x32_bf16 v[102:105], v[184:187], v[216:219], v[102:105]
	v_mfma_f32_16x16x32_bf16 v[98:101], v[192:195], v[216:219], v[98:101]
	v_mfma_f32_16x16x32_bf16 v[86:89], v[184:187], v[224:227], v[86:89]
	v_mfma_f32_16x16x32_bf16 v[82:85], v[192:195], v[224:227], v[82:85]
	v_mfma_f32_16x16x32_bf16 v[70:73], v[184:187], v[232:235], v[70:73]
	v_mfma_f32_16x16x32_bf16 v[66:69], v[192:195], v[232:235], v[66:69]
	v_mfma_f32_16x16x32_bf16 v[118:121], v[188:191], v[212:215], v[118:121]
	v_mfma_f32_16x16x32_bf16 v[114:117], v[204:207], v[212:215], v[114:117]
	v_mfma_f32_16x16x32_bf16 v[102:105], v[188:191], v[220:223], v[102:105]
	v_mfma_f32_16x16x32_bf16 v[98:101], v[204:207], v[220:223], v[98:101]
	v_mfma_f32_16x16x32_bf16 v[86:89], v[188:191], v[228:231], v[86:89]
	v_mfma_f32_16x16x32_bf16 v[82:85], v[204:207], v[228:231], v[82:85]
	v_mfma_f32_16x16x32_bf16 v[70:73], v[188:191], v[236:239], v[70:73]
	v_mfma_f32_16x16x32_bf16 v[66:69], v[204:207], v[236:239], v[66:69]
	s_setprio 0
	s_barrier
	s_mov_b32 m0, s44
	s_add_u32 s56, s24, 0x2b0000
	global_load_lds_dwordx4 v132, s[24:25]
	s_mov_b32 m0, s45
	s_addc_u32 s57, s25, 0
	global_load_lds_dwordx4 v136, s[24:25]
	s_mov_b32 m0, s46
	ds_read_b128 v[208:211], v158 offset:16384
	global_load_lds_dwordx4 v132, s[56:57]
	s_mov_b32 m0, s47
	ds_read_b128 v[212:215], v158 offset:17408
	global_load_lds_dwordx4 v136, s[56:57]
	ds_read_b128 v[216:219], v158 offset:18432
	ds_read_b128 v[220:223], v158 offset:19456
	ds_read_b128 v[224:227], v158 offset:20480
	ds_read_b128 v[228:231], v158 offset:21504
	ds_read_b128 v[232:235], v158 offset:22528
	ds_read_b128 v[236:239], v158 offset:23552
	s_waitcnt vmcnt(6)
	s_waitcnt lgkmcnt(0)
	s_barrier
	s_setprio 1
	s_waitcnt lgkmcnt(0)
	v_mfma_f32_16x16x32_bf16 v[62:65], v[142:145], v[208:211], v[62:65]
	v_mfma_f32_16x16x32_bf16 v[58:61], v[176:179], v[208:211], v[58:61]
	v_mfma_f32_16x16x32_bf16 v[46:49], v[142:145], v[216:219], v[46:49]
	v_mfma_f32_16x16x32_bf16 v[42:45], v[176:179], v[216:219], v[42:45]
	v_mfma_f32_16x16x32_bf16 v[30:33], v[142:145], v[224:227], v[30:33]
	v_mfma_f32_16x16x32_bf16 v[26:29], v[176:179], v[224:227], v[26:29]
	v_mfma_f32_16x16x32_bf16 v[14:17], v[142:145], v[232:235], v[14:17]
	v_mfma_f32_16x16x32_bf16 v[10:13], v[176:179], v[232:235], v[10:13]
	v_mfma_f32_16x16x32_bf16 v[62:65], v[168:171], v[212:215], v[62:65]
	v_mfma_f32_16x16x32_bf16 v[58:61], v[180:183], v[212:215], v[58:61]
	v_mfma_f32_16x16x32_bf16 v[46:49], v[168:171], v[220:223], v[46:49]
	v_mfma_f32_16x16x32_bf16 v[42:45], v[180:183], v[220:223], v[42:45]
	v_mfma_f32_16x16x32_bf16 v[30:33], v[168:171], v[228:231], v[30:33]
	v_mfma_f32_16x16x32_bf16 v[26:29], v[180:183], v[228:231], v[26:29]
	v_mfma_f32_16x16x32_bf16 v[14:17], v[168:171], v[236:239], v[14:17]
	v_mfma_f32_16x16x32_bf16 v[10:13], v[180:183], v[236:239], v[10:13]
	s_setprio 0
	s_setprio 1
	v_mfma_f32_16x16x32_bf16 v[54:57], v[184:187], v[208:211], v[54:57]
	v_mfma_f32_16x16x32_bf16 v[50:53], v[192:195], v[208:211], v[50:53]
	v_mfma_f32_16x16x32_bf16 v[38:41], v[184:187], v[216:219], v[38:41]
	v_mfma_f32_16x16x32_bf16 v[34:37], v[192:195], v[216:219], v[34:37]
	v_mfma_f32_16x16x32_bf16 v[22:25], v[184:187], v[224:227], v[22:25]
	v_mfma_f32_16x16x32_bf16 v[18:21], v[192:195], v[224:227], v[18:21]
	v_mfma_f32_16x16x32_bf16 v[6:9], v[184:187], v[232:235], v[6:9]
	v_mfma_f32_16x16x32_bf16 v[2:5], v[192:195], v[232:235], v[2:5]
	v_mfma_f32_16x16x32_bf16 v[54:57], v[188:191], v[212:215], v[54:57]
	v_mfma_f32_16x16x32_bf16 v[50:53], v[204:207], v[212:215], v[50:53]
	v_mfma_f32_16x16x32_bf16 v[38:41], v[188:191], v[220:223], v[38:41]
	v_mfma_f32_16x16x32_bf16 v[34:37], v[204:207], v[220:223], v[34:37]
	v_mfma_f32_16x16x32_bf16 v[22:25], v[188:191], v[228:231], v[22:25]
	v_mfma_f32_16x16x32_bf16 v[18:21], v[204:207], v[228:231], v[18:21]
	v_mfma_f32_16x16x32_bf16 v[6:9], v[188:191], v[236:239], v[6:9]
	v_mfma_f32_16x16x32_bf16 v[2:5], v[204:207], v[236:239], v[2:5]
	s_setprio 0
	s_barrier
	s_mov_b32 m0, s35
	ds_read_b128 v[142:145], v159
	global_load_lds_dwordx4 v130, s[26:27]
	s_mov_b32 m0, s36
	ds_read_b128 v[168:171], v159 offset:1024
	global_load_lds_dwordx4 v134, s[26:27]
	s_add_u32 s26, s26, 0x2b0000
	s_addc_u32 s27, s27, 0
	s_mov_b32 m0, s37
	ds_read_b128 v[176:179], v159 offset:2048
	global_load_lds_dwordx4 v130, s[26:27]
	s_mov_b32 m0, s38
	ds_read_b128 v[180:183], v159 offset:3072
	global_load_lds_dwordx4 v134, s[26:27]
	ds_read_b128 v[184:187], v160
	ds_read_b128 v[188:191], v160 offset:1024
	ds_read_b128 v[192:195], v160 offset:2048
	ds_read_b128 v[204:207], v160 offset:3072
	ds_read_b128 v[208:211], v158 offset:32768
	ds_read_b128 v[212:215], v158 offset:33792
	ds_read_b128 v[216:219], v158 offset:34816
	ds_read_b128 v[220:223], v158 offset:35840
	ds_read_b128 v[224:227], v158 offset:36864
	ds_read_b128 v[228:231], v158 offset:37888
	ds_read_b128 v[232:235], v158 offset:38912
	ds_read_b128 v[236:239], v158 offset:39936
	s_waitcnt vmcnt(8)
	s_waitcnt lgkmcnt(0)
	s_barrier
	s_setprio 1
	s_waitcnt lgkmcnt(0)
	v_mfma_f32_16x16x32_bf16 v[126:129], v[142:145], v[208:211], v[126:129]
	v_mfma_f32_16x16x32_bf16 v[122:125], v[176:179], v[208:211], v[122:125]
	v_mfma_f32_16x16x32_bf16 v[110:113], v[142:145], v[216:219], v[110:113]
	v_mfma_f32_16x16x32_bf16 v[106:109], v[176:179], v[216:219], v[106:109]
	v_mfma_f32_16x16x32_bf16 v[94:97], v[142:145], v[224:227], v[94:97]
	v_mfma_f32_16x16x32_bf16 v[90:93], v[176:179], v[224:227], v[90:93]
	v_mfma_f32_16x16x32_bf16 v[78:81], v[142:145], v[232:235], v[78:81]
	v_mfma_f32_16x16x32_bf16 v[74:77], v[176:179], v[232:235], v[74:77]
	v_mfma_f32_16x16x32_bf16 v[126:129], v[168:171], v[212:215], v[126:129]
	v_mfma_f32_16x16x32_bf16 v[122:125], v[180:183], v[212:215], v[122:125]
	v_mfma_f32_16x16x32_bf16 v[110:113], v[168:171], v[220:223], v[110:113]
	v_mfma_f32_16x16x32_bf16 v[106:109], v[180:183], v[220:223], v[106:109]
	v_mfma_f32_16x16x32_bf16 v[94:97], v[168:171], v[228:231], v[94:97]
	v_mfma_f32_16x16x32_bf16 v[90:93], v[180:183], v[228:231], v[90:93]
	v_mfma_f32_16x16x32_bf16 v[78:81], v[168:171], v[236:239], v[78:81]
	v_mfma_f32_16x16x32_bf16 v[74:77], v[180:183], v[236:239], v[74:77]
	s_setprio 0
	s_setprio 1
	v_mfma_f32_16x16x32_bf16 v[118:121], v[184:187], v[208:211], v[118:121]
	v_mfma_f32_16x16x32_bf16 v[114:117], v[192:195], v[208:211], v[114:117]
	v_mfma_f32_16x16x32_bf16 v[102:105], v[184:187], v[216:219], v[102:105]
	v_mfma_f32_16x16x32_bf16 v[98:101], v[192:195], v[216:219], v[98:101]
	v_mfma_f32_16x16x32_bf16 v[86:89], v[184:187], v[224:227], v[86:89]
	v_mfma_f32_16x16x32_bf16 v[82:85], v[192:195], v[224:227], v[82:85]
	v_mfma_f32_16x16x32_bf16 v[70:73], v[184:187], v[232:235], v[70:73]
	v_mfma_f32_16x16x32_bf16 v[66:69], v[192:195], v[232:235], v[66:69]
	v_mfma_f32_16x16x32_bf16 v[118:121], v[188:191], v[212:215], v[118:121]
	v_mfma_f32_16x16x32_bf16 v[114:117], v[204:207], v[212:215], v[114:117]
	v_mfma_f32_16x16x32_bf16 v[102:105], v[188:191], v[220:223], v[102:105]
	v_mfma_f32_16x16x32_bf16 v[98:101], v[204:207], v[220:223], v[98:101]
	v_mfma_f32_16x16x32_bf16 v[86:89], v[188:191], v[228:231], v[86:89]
	v_mfma_f32_16x16x32_bf16 v[82:85], v[204:207], v[228:231], v[82:85]
	v_mfma_f32_16x16x32_bf16 v[70:73], v[188:191], v[236:239], v[70:73]
	v_mfma_f32_16x16x32_bf16 v[66:69], v[204:207], v[236:239], v[66:69]
	s_setprio 0
	s_barrier
	s_mov_b32 m0, s48
	s_add_u32 s24, s24, 0x80
	s_addc_u32 s25, s25, 0
	global_load_lds_dwordx4 v132, s[24:25]
	s_mov_b32 m0, s49
	ds_read_b128 v[208:211], v158 offset:49152
	global_load_lds_dwordx4 v136, s[24:25]
	s_mov_b32 m0, s50
	s_add_u32 s24, s24, 0x2b0000
	s_addc_u32 s25, s25, 0
	global_load_lds_dwordx4 v132, s[24:25]
	s_add_i32 m0, s50, 0x2000
	ds_read_b128 v[212:215], v158 offset:50176
	global_load_lds_dwordx4 v136, s[24:25]
	ds_read_b128 v[216:219], v158 offset:51200
	ds_read_b128 v[220:223], v158 offset:52224
	ds_read_b128 v[224:227], v158 offset:53248
	ds_read_b128 v[228:231], v158 offset:54272
	ds_read_b128 v[232:235], v158 offset:55296
	ds_read_b128 v[236:239], v158 offset:56320
	s_waitcnt vmcnt(6)
	s_waitcnt lgkmcnt(0)
	s_barrier
	s_setprio 1
	s_waitcnt lgkmcnt(0)
	v_mfma_f32_16x16x32_bf16 v[62:65], v[142:145], v[208:211], v[62:65]
	v_mfma_f32_16x16x32_bf16 v[58:61], v[176:179], v[208:211], v[58:61]
	v_mfma_f32_16x16x32_bf16 v[46:49], v[142:145], v[216:219], v[46:49]
	v_mfma_f32_16x16x32_bf16 v[42:45], v[176:179], v[216:219], v[42:45]
	v_mfma_f32_16x16x32_bf16 v[30:33], v[142:145], v[224:227], v[30:33]
	v_mfma_f32_16x16x32_bf16 v[26:29], v[176:179], v[224:227], v[26:29]
	v_mfma_f32_16x16x32_bf16 v[14:17], v[142:145], v[232:235], v[14:17]
	v_mfma_f32_16x16x32_bf16 v[10:13], v[176:179], v[232:235], v[10:13]
	v_mfma_f32_16x16x32_bf16 v[62:65], v[168:171], v[212:215], v[62:65]
	v_mfma_f32_16x16x32_bf16 v[58:61], v[180:183], v[212:215], v[58:61]
	v_mfma_f32_16x16x32_bf16 v[46:49], v[168:171], v[220:223], v[46:49]
	v_mfma_f32_16x16x32_bf16 v[42:45], v[180:183], v[220:223], v[42:45]
	v_mfma_f32_16x16x32_bf16 v[30:33], v[168:171], v[228:231], v[30:33]
	v_mfma_f32_16x16x32_bf16 v[26:29], v[180:183], v[228:231], v[26:29]
	v_mfma_f32_16x16x32_bf16 v[14:17], v[168:171], v[236:239], v[14:17]
	v_mfma_f32_16x16x32_bf16 v[10:13], v[180:183], v[236:239], v[10:13]
	s_setprio 0
	s_setprio 1
	v_mfma_f32_16x16x32_bf16 v[54:57], v[184:187], v[208:211], v[54:57]
	v_mfma_f32_16x16x32_bf16 v[50:53], v[192:195], v[208:211], v[50:53]
	v_mfma_f32_16x16x32_bf16 v[38:41], v[184:187], v[216:219], v[38:41]
	v_mfma_f32_16x16x32_bf16 v[34:37], v[192:195], v[216:219], v[34:37]
	v_mfma_f32_16x16x32_bf16 v[22:25], v[184:187], v[224:227], v[22:25]
	v_mfma_f32_16x16x32_bf16 v[18:21], v[192:195], v[224:227], v[18:21]
	v_mfma_f32_16x16x32_bf16 v[6:9], v[184:187], v[232:235], v[6:9]
	v_mfma_f32_16x16x32_bf16 v[2:5], v[192:195], v[232:235], v[2:5]
	v_mfma_f32_16x16x32_bf16 v[54:57], v[188:191], v[212:215], v[54:57]
	v_mfma_f32_16x16x32_bf16 v[50:53], v[204:207], v[212:215], v[50:53]
	v_mfma_f32_16x16x32_bf16 v[38:41], v[188:191], v[220:223], v[38:41]
	v_mfma_f32_16x16x32_bf16 v[34:37], v[204:207], v[220:223], v[34:37]
	v_mfma_f32_16x16x32_bf16 v[22:25], v[188:191], v[228:231], v[22:25]
	v_mfma_f32_16x16x32_bf16 v[18:21], v[204:207], v[228:231], v[18:21]
	v_mfma_f32_16x16x32_bf16 v[6:9], v[188:191], v[236:239], v[6:9]
	v_mfma_f32_16x16x32_bf16 v[2:5], v[204:207], v[236:239], v[2:5]
	s_setprio 0
	s_barrier
	s_add_i32 s55, s55, 2
	s_add_u32 s22, s22, 0x100
	s_addc_u32 s23, s23, 0
	s_add_u32 s53, s53, 0x100
	s_addc_u32 s54, s54, 0
	s_cmpk_gt_u32 s55, 0xa9
	s_cbranch_scc0 .LBB0_1418
	s_and_b64 vcc, exec, s[14:15]
	s_cbranch_vccz .LBB0_1421
	s_barrier

.LBB0_2373:
	s_add_u32 s60, s20, 0xfff00000
	s_addc_u32 s61, s21, -1
	s_mov_b32 m0, s35
	ds_read_b128 v[142:145], v148
	global_load_lds_dwordx4 v130, s[60:61]
	s_mov_b32 m0, s36
	ds_read_b128 v[154:157], v148 offset:1024
	global_load_lds_dwordx4 v134, s[60:61]
	s_mov_b32 m0, s40
	ds_read_b128 v[158:161], v148 offset:2048
	global_load_lds_dwordx4 v138, s[20:21]
	s_mov_b32 m0, s41
	ds_read_b128 v[168:171], v148 offset:3072
	global_load_lds_dwordx4 v140, s[20:21]
	ds_read_b128 v[176:179], v149
	ds_read_b128 v[180:183], v149 offset:1024
	ds_read_b128 v[184:187], v149 offset:2048
	ds_read_b128 v[188:191], v149 offset:3072
	s_add_u32 s22, s20, 0xfff00080
	s_addc_u32 s23, s21, -1
	s_cmp_eq_u32 s57, 60
	s_cselect_b32 s25, s52, s23
	s_cselect_b32 s24, s53, s22
	s_cselect_b32 s23, s7, s56
	s_cselect_b32 s22, s54, s55
	ds_read_b128 v[192:195], v150
	ds_read_b128 v[204:207], v150 offset:1024
	ds_read_b128 v[208:211], v150 offset:2048
	ds_read_b128 v[212:215], v150 offset:3072
	ds_read_b128 v[216:219], v150 offset:4096
	ds_read_b128 v[220:223], v150 offset:5120
	ds_read_b128 v[224:227], v150 offset:6144
	ds_read_b128 v[228:231], v150 offset:7168
	s_waitcnt vmcnt(8)
	s_waitcnt lgkmcnt(0)
	s_barrier
	s_setprio 1
	s_waitcnt lgkmcnt(0)
	v_mfma_f32_16x16x32_bf16 v[126:129], v[142:145], v[192:195], v[126:129]
	v_mfma_f32_16x16x32_bf16 v[122:125], v[158:161], v[192:195], v[122:125]
	v_mfma_f32_16x16x32_bf16 v[110:113], v[142:145], v[208:211], v[110:113]
	v_mfma_f32_16x16x32_bf16 v[106:109], v[158:161], v[208:211], v[106:109]
	v_mfma_f32_16x16x32_bf16 v[94:97], v[142:145], v[216:219], v[94:97]
	v_mfma_f32_16x16x32_bf16 v[90:93], v[158:161], v[216:219], v[90:93]
	v_mfma_f32_16x16x32_bf16 v[78:81], v[142:145], v[224:227], v[78:81]
	v_mfma_f32_16x16x32_bf16 v[74:77], v[158:161], v[224:227], v[74:77]
	v_mfma_f32_16x16x32_bf16 v[126:129], v[154:157], v[204:207], v[126:129]
	v_mfma_f32_16x16x32_bf16 v[122:125], v[168:171], v[204:207], v[122:125]
	v_mfma_f32_16x16x32_bf16 v[110:113], v[154:157], v[212:215], v[110:113]
	v_mfma_f32_16x16x32_bf16 v[106:109], v[168:171], v[212:215], v[106:109]
	v_mfma_f32_16x16x32_bf16 v[94:97], v[154:157], v[220:223], v[94:97]
	v_mfma_f32_16x16x32_bf16 v[90:93], v[168:171], v[220:223], v[90:93]
	v_mfma_f32_16x16x32_bf16 v[78:81], v[154:157], v[228:231], v[78:81]
	v_mfma_f32_16x16x32_bf16 v[74:77], v[168:171], v[228:231], v[74:77]
	s_setprio 0
	s_setprio 1
	v_mfma_f32_16x16x32_bf16 v[118:121], v[176:179], v[192:195], v[118:121]
	v_mfma_f32_16x16x32_bf16 v[114:117], v[184:187], v[192:195], v[114:117]
	v_mfma_f32_16x16x32_bf16 v[102:105], v[176:179], v[208:211], v[102:105]
	v_mfma_f32_16x16x32_bf16 v[98:101], v[184:187], v[208:211], v[98:101]
	v_mfma_f32_16x16x32_bf16 v[86:89], v[176:179], v[216:219], v[86:89]
	v_mfma_f32_16x16x32_bf16 v[82:85], v[184:187], v[216:219], v[82:85]
	v_mfma_f32_16x16x32_bf16 v[70:73], v[176:179], v[224:227], v[70:73]
	v_mfma_f32_16x16x32_bf16 v[66:69], v[184:187], v[224:227], v[66:69]
	v_mfma_f32_16x16x32_bf16 v[118:121], v[180:183], v[204:207], v[118:121]
	v_mfma_f32_16x16x32_bf16 v[114:117], v[188:191], v[204:207], v[114:117]
	v_mfma_f32_16x16x32_bf16 v[102:105], v[180:183], v[212:215], v[102:105]
	v_mfma_f32_16x16x32_bf16 v[98:101], v[188:191], v[212:215], v[98:101]
	v_mfma_f32_16x16x32_bf16 v[86:89], v[180:183], v[220:223], v[86:89]
	v_mfma_f32_16x16x32_bf16 v[82:85], v[188:191], v[220:223], v[82:85]
	v_mfma_f32_16x16x32_bf16 v[70:73], v[180:183], v[228:231], v[70:73]
	v_mfma_f32_16x16x32_bf16 v[66:69], v[188:191], v[228:231], v[66:69]
	s_setprio 0
	s_barrier
	s_mov_b32 m0, s42
	s_add_u32 s60, s22, 0x100000
	global_load_lds_dwordx4 v132, s[22:23]
	s_mov_b32 m0, s43
	s_addc_u32 s61, s23, 0
	global_load_lds_dwordx4 v136, s[22:23]
	s_mov_b32 m0, s44
	ds_read_b128 v[192:195], v150 offset:16384
	global_load_lds_dwordx4 v132, s[60:61]
	s_mov_b32 m0, s45
	ds_read_b128 v[204:207], v150 offset:17408
	global_load_lds_dwordx4 v136, s[60:61]
	ds_read_b128 v[208:211], v150 offset:18432
	ds_read_b128 v[212:215], v150 offset:19456
	ds_read_b128 v[216:219], v150 offset:20480
	ds_read_b128 v[220:223], v150 offset:21504
	ds_read_b128 v[224:227], v150 offset:22528
	ds_read_b128 v[228:231], v150 offset:23552
	s_waitcnt vmcnt(6)
	s_waitcnt lgkmcnt(0)
	s_barrier
	s_setprio 1
	s_waitcnt lgkmcnt(0)
	v_mfma_f32_16x16x32_bf16 v[62:65], v[142:145], v[192:195], v[62:65]
	v_mfma_f32_16x16x32_bf16 v[58:61], v[158:161], v[192:195], v[58:61]
	v_mfma_f32_16x16x32_bf16 v[46:49], v[142:145], v[208:211], v[46:49]
	v_mfma_f32_16x16x32_bf16 v[42:45], v[158:161], v[208:211], v[42:45]
	v_mfma_f32_16x16x32_bf16 v[30:33], v[142:145], v[216:219], v[30:33]
	v_mfma_f32_16x16x32_bf16 v[26:29], v[158:161], v[216:219], v[26:29]
	v_mfma_f32_16x16x32_bf16 v[14:17], v[142:145], v[224:227], v[14:17]
	v_mfma_f32_16x16x32_bf16 v[10:13], v[158:161], v[224:227], v[10:13]
	v_mfma_f32_16x16x32_bf16 v[62:65], v[154:157], v[204:207], v[62:65]
	v_mfma_f32_16x16x32_bf16 v[58:61], v[168:171], v[204:207], v[58:61]
	v_mfma_f32_16x16x32_bf16 v[46:49], v[154:157], v[212:215], v[46:49]
	v_mfma_f32_16x16x32_bf16 v[42:45], v[168:171], v[212:215], v[42:45]
	v_mfma_f32_16x16x32_bf16 v[30:33], v[154:157], v[220:223], v[30:33]
	v_mfma_f32_16x16x32_bf16 v[26:29], v[168:171], v[220:223], v[26:29]
	v_mfma_f32_16x16x32_bf16 v[14:17], v[154:157], v[228:231], v[14:17]
	v_mfma_f32_16x16x32_bf16 v[10:13], v[168:171], v[228:231], v[10:13]
	s_setprio 0
	s_setprio 1
	v_mfma_f32_16x16x32_bf16 v[54:57], v[176:179], v[192:195], v[54:57]
	v_mfma_f32_16x16x32_bf16 v[50:53], v[184:187], v[192:195], v[50:53]
	v_mfma_f32_16x16x32_bf16 v[38:41], v[176:179], v[208:211], v[38:41]
	v_mfma_f32_16x16x32_bf16 v[34:37], v[184:187], v[208:211], v[34:37]
	v_mfma_f32_16x16x32_bf16 v[22:25], v[176:179], v[216:219], v[22:25]
	v_mfma_f32_16x16x32_bf16 v[18:21], v[184:187], v[216:219], v[18:21]
	v_mfma_f32_16x16x32_bf16 v[6:9], v[176:179], v[224:227], v[6:9]
	v_mfma_f32_16x16x32_bf16 v[2:5], v[184:187], v[224:227], v[2:5]
	v_mfma_f32_16x16x32_bf16 v[54:57], v[180:183], v[204:207], v[54:57]
	v_mfma_f32_16x16x32_bf16 v[50:53], v[188:191], v[204:207], v[50:53]
	v_mfma_f32_16x16x32_bf16 v[38:41], v[180:183], v[212:215], v[38:41]
	v_mfma_f32_16x16x32_bf16 v[34:37], v[188:191], v[212:215], v[34:37]
	v_mfma_f32_16x16x32_bf16 v[22:25], v[180:183], v[220:223], v[22:25]
	v_mfma_f32_16x16x32_bf16 v[18:21], v[188:191], v[220:223], v[18:21]
	v_mfma_f32_16x16x32_bf16 v[6:9], v[180:183], v[228:231], v[6:9]
	v_mfma_f32_16x16x32_bf16 v[2:5], v[188:191], v[228:231], v[2:5]
	s_setprio 0
	s_barrier
	s_mov_b32 m0, s29
	ds_read_b128 v[142:145], v151
	global_load_lds_dwordx4 v130, s[24:25]
	s_mov_b32 m0, s30
	ds_read_b128 v[154:157], v151 offset:1024
	global_load_lds_dwordx4 v134, s[24:25]
	s_add_u32 s24, s24, 0x100000
	s_addc_u32 s25, s25, 0
	s_mov_b32 m0, s31
	ds_read_b128 v[158:161], v151 offset:2048
	global_load_lds_dwordx4 v130, s[24:25]
	s_mov_b32 m0, s33
	ds_read_b128 v[168:171], v151 offset:3072
	global_load_lds_dwordx4 v134, s[24:25]
	ds_read_b128 v[176:179], v152
	ds_read_b128 v[180:183], v152 offset:1024
	ds_read_b128 v[184:187], v152 offset:2048
	ds_read_b128 v[188:191], v152 offset:3072
	ds_read_b128 v[192:195], v150 offset:32768
	ds_read_b128 v[204:207], v150 offset:33792
	ds_read_b128 v[208:211], v150 offset:34816
	ds_read_b128 v[212:215], v150 offset:35840
	ds_read_b128 v[216:219], v150 offset:36864
	ds_read_b128 v[220:223], v150 offset:37888
	ds_read_b128 v[224:227], v150 offset:38912
	ds_read_b128 v[228:231], v150 offset:39936
	s_waitcnt vmcnt(8)
	s_waitcnt lgkmcnt(0)
	s_barrier
	s_setprio 1
	s_waitcnt lgkmcnt(0)
	v_mfma_f32_16x16x32_bf16 v[126:129], v[142:145], v[192:195], v[126:129]
	v_mfma_f32_16x16x32_bf16 v[122:125], v[158:161], v[192:195], v[122:125]
	v_mfma_f32_16x16x32_bf16 v[110:113], v[142:145], v[208:211], v[110:113]
	v_mfma_f32_16x16x32_bf16 v[106:109], v[158:161], v[208:211], v[106:109]
	v_mfma_f32_16x16x32_bf16 v[94:97], v[142:145], v[216:219], v[94:97]
	v_mfma_f32_16x16x32_bf16 v[90:93], v[158:161], v[216:219], v[90:93]
	v_mfma_f32_16x16x32_bf16 v[78:81], v[142:145], v[224:227], v[78:81]
	v_mfma_f32_16x16x32_bf16 v[74:77], v[158:161], v[224:227], v[74:77]
	v_mfma_f32_16x16x32_bf16 v[126:129], v[154:157], v[204:207], v[126:129]
	v_mfma_f32_16x16x32_bf16 v[122:125], v[168:171], v[204:207], v[122:125]
	v_mfma_f32_16x16x32_bf16 v[110:113], v[154:157], v[212:215], v[110:113]
	v_mfma_f32_16x16x32_bf16 v[106:109], v[168:171], v[212:215], v[106:109]
	v_mfma_f32_16x16x32_bf16 v[94:97], v[154:157], v[220:223], v[94:97]
	v_mfma_f32_16x16x32_bf16 v[90:93], v[168:171], v[220:223], v[90:93]
	v_mfma_f32_16x16x32_bf16 v[78:81], v[154:157], v[228:231], v[78:81]
	v_mfma_f32_16x16x32_bf16 v[74:77], v[168:171], v[228:231], v[74:77]
	s_setprio 0
	s_setprio 1
	v_mfma_f32_16x16x32_bf16 v[118:121], v[176:179], v[192:195], v[118:121]
	v_mfma_f32_16x16x32_bf16 v[114:117], v[184:187], v[192:195], v[114:117]
	v_mfma_f32_16x16x32_bf16 v[102:105], v[176:179], v[208:211], v[102:105]
	v_mfma_f32_16x16x32_bf16 v[98:101], v[184:187], v[208:211], v[98:101]
	v_mfma_f32_16x16x32_bf16 v[86:89], v[176:179], v[216:219], v[86:89]
	v_mfma_f32_16x16x32_bf16 v[82:85], v[184:187], v[216:219], v[82:85]
	v_mfma_f32_16x16x32_bf16 v[70:73], v[176:179], v[224:227], v[70:73]
	v_mfma_f32_16x16x32_bf16 v[66:69], v[184:187], v[224:227], v[66:69]
	v_mfma_f32_16x16x32_bf16 v[118:121], v[180:183], v[204:207], v[118:121]
	v_mfma_f32_16x16x32_bf16 v[114:117], v[188:191], v[204:207], v[114:117]
	v_mfma_f32_16x16x32_bf16 v[102:105], v[180:183], v[212:215], v[102:105]
	v_mfma_f32_16x16x32_bf16 v[98:101], v[188:191], v[212:215], v[98:101]
	v_mfma_f32_16x16x32_bf16 v[86:89], v[180:183], v[220:223], v[86:89]
	v_mfma_f32_16x16x32_bf16 v[82:85], v[188:191], v[220:223], v[82:85]
	v_mfma_f32_16x16x32_bf16 v[70:73], v[180:183], v[228:231], v[70:73]
	v_mfma_f32_16x16x32_bf16 v[66:69], v[188:191], v[228:231], v[66:69]
	s_setprio 0
	s_barrier
	s_mov_b32 m0, s46
	s_add_u32 s22, s22, 0x80
	s_addc_u32 s23, s23, 0
	global_load_lds_dwordx4 v132, s[22:23]
	s_mov_b32 m0, s47
	ds_read_b128 v[192:195], v150 offset:49152
	global_load_lds_dwordx4 v136, s[22:23]
	s_mov_b32 m0, s48
	s_add_u32 s22, s22, 0x100000
	s_addc_u32 s23, s23, 0
	global_load_lds_dwordx4 v132, s[22:23]
	s_mov_b32 m0, s49
	ds_read_b128 v[204:207], v150 offset:50176
	global_load_lds_dwordx4 v136, s[22:23]
	ds_read_b128 v[208:211], v150 offset:51200
	ds_read_b128 v[212:215], v150 offset:52224
	ds_read_b128 v[216:219], v150 offset:53248
	ds_read_b128 v[220:223], v150 offset:54272
	ds_read_b128 v[224:227], v150 offset:55296
	ds_read_b128 v[228:231], v150 offset:56320
	s_waitcnt vmcnt(6)
	s_waitcnt lgkmcnt(0)
	s_barrier
	s_setprio 1
	s_waitcnt lgkmcnt(0)
	v_mfma_f32_16x16x32_bf16 v[62:65], v[142:145], v[192:195], v[62:65]
	v_mfma_f32_16x16x32_bf16 v[58:61], v[158:161], v[192:195], v[58:61]
	v_mfma_f32_16x16x32_bf16 v[46:49], v[142:145], v[208:211], v[46:49]
	v_mfma_f32_16x16x32_bf16 v[42:45], v[158:161], v[208:211], v[42:45]
	v_mfma_f32_16x16x32_bf16 v[30:33], v[142:145], v[216:219], v[30:33]
	v_mfma_f32_16x16x32_bf16 v[26:29], v[158:161], v[216:219], v[26:29]
	v_mfma_f32_16x16x32_bf16 v[14:17], v[142:145], v[224:227], v[14:17]
	v_mfma_f32_16x16x32_bf16 v[10:13], v[158:161], v[224:227], v[10:13]
	v_mfma_f32_16x16x32_bf16 v[62:65], v[154:157], v[204:207], v[62:65]
	v_mfma_f32_16x16x32_bf16 v[58:61], v[168:171], v[204:207], v[58:61]
	v_mfma_f32_16x16x32_bf16 v[46:49], v[154:157], v[212:215], v[46:49]
	v_mfma_f32_16x16x32_bf16 v[42:45], v[168:171], v[212:215], v[42:45]
	v_mfma_f32_16x16x32_bf16 v[30:33], v[154:157], v[220:223], v[30:33]
	v_mfma_f32_16x16x32_bf16 v[26:29], v[168:171], v[220:223], v[26:29]
	v_mfma_f32_16x16x32_bf16 v[14:17], v[154:157], v[228:231], v[14:17]
	v_mfma_f32_16x16x32_bf16 v[10:13], v[168:171], v[228:231], v[10:13]
	s_setprio 0
	s_setprio 1
	v_mfma_f32_16x16x32_bf16 v[54:57], v[176:179], v[192:195], v[54:57]
	v_mfma_f32_16x16x32_bf16 v[50:53], v[184:187], v[192:195], v[50:53]
	v_mfma_f32_16x16x32_bf16 v[38:41], v[176:179], v[208:211], v[38:41]
	v_mfma_f32_16x16x32_bf16 v[34:37], v[184:187], v[208:211], v[34:37]
	v_mfma_f32_16x16x32_bf16 v[22:25], v[176:179], v[216:219], v[22:25]
	v_mfma_f32_16x16x32_bf16 v[18:21], v[184:187], v[216:219], v[18:21]
	v_mfma_f32_16x16x32_bf16 v[6:9], v[176:179], v[224:227], v[6:9]
	v_mfma_f32_16x16x32_bf16 v[2:5], v[184:187], v[224:227], v[2:5]
	v_mfma_f32_16x16x32_bf16 v[54:57], v[180:183], v[204:207], v[54:57]
	v_mfma_f32_16x16x32_bf16 v[50:53], v[188:191], v[204:207], v[50:53]
	v_mfma_f32_16x16x32_bf16 v[38:41], v[180:183], v[212:215], v[38:41]
	v_mfma_f32_16x16x32_bf16 v[34:37], v[188:191], v[212:215], v[34:37]
	v_mfma_f32_16x16x32_bf16 v[22:25], v[180:183], v[220:223], v[22:25]
	v_mfma_f32_16x16x32_bf16 v[18:21], v[188:191], v[220:223], v[18:21]
	v_mfma_f32_16x16x32_bf16 v[6:9], v[180:183], v[228:231], v[6:9]
	v_mfma_f32_16x16x32_bf16 v[2:5], v[188:191], v[228:231], v[2:5]
	s_setprio 0
	s_barrier
	s_add_i32 s57, s57, 2
	s_add_u32 s20, s20, 0x100
	s_addc_u32 s21, s21, 0
	s_add_u32 s55, s55, 0x100
	s_addc_u32 s56, s56, 0
	s_cmp_gt_u32 s57, 61
	s_cbranch_scc0 .LBB0_2373
	s_and_b64 vcc, exec, s[16:17]
	s_cbranch_vccz .LBB0_2376
	s_barrier

.LBB0_2618:
	s_add_u32 s64, s28, 0xffd50000
	s_addc_u32 s65, s29, -1
	s_mov_b32 m0, s44
	ds_read_b128 v[142:145], v156
	global_load_lds_dwordx4 v130, s[64:65]
	s_mov_b32 m0, s45
	ds_read_b128 v[168:171], v156 offset:1024
	global_load_lds_dwordx4 v134, s[64:65]
	s_mov_b32 m0, s46
	ds_read_b128 v[172:175], v156 offset:2048
	global_load_lds_dwordx4 v138, s[28:29]
	s_mov_b32 m0, s47
	ds_read_b128 v[176:179], v156 offset:3072
	global_load_lds_dwordx4 v140, s[28:29]
	ds_read_b128 v[180:183], v157
	ds_read_b128 v[184:187], v157 offset:1024
	ds_read_b128 v[188:191], v157 offset:2048
	ds_read_b128 v[192:195], v157 offset:3072
	s_add_u32 s30, s28, 0xffd50080
	s_addc_u32 s31, s29, -1
	s_cmpk_eq_i32 s62, 0xa8
	s_cselect_b32 s35, s25, s31
	s_cselect_b32 s34, s24, s30
	s_cselect_b32 s31, s23, s61
	s_cselect_b32 s30, s22, s60
	ds_read_b128 v[196:199], v158
	ds_read_b128 v[200:203], v158 offset:1024
	ds_read_b128 v[204:207], v158 offset:2048
	ds_read_b128 v[208:211], v158 offset:3072
	ds_read_b128 v[212:215], v158 offset:4096
	ds_read_b128 v[216:219], v158 offset:5120
	ds_read_b128 v[220:223], v158 offset:6144
	ds_read_b128 v[224:227], v158 offset:7168
	s_waitcnt vmcnt(8)
	s_waitcnt lgkmcnt(0)
	s_barrier
	s_setprio 1
	s_waitcnt lgkmcnt(0)
	v_mfma_f32_16x16x32_bf16 v[126:129], v[142:145], v[196:199], v[126:129]
	v_mfma_f32_16x16x32_bf16 v[122:125], v[172:175], v[196:199], v[122:125]
	v_mfma_f32_16x16x32_bf16 v[110:113], v[142:145], v[204:207], v[110:113]
	v_mfma_f32_16x16x32_bf16 v[106:109], v[172:175], v[204:207], v[106:109]
	v_mfma_f32_16x16x32_bf16 v[94:97], v[142:145], v[212:215], v[94:97]
	v_mfma_f32_16x16x32_bf16 v[90:93], v[172:175], v[212:215], v[90:93]
	v_mfma_f32_16x16x32_bf16 v[78:81], v[142:145], v[220:223], v[78:81]
	v_mfma_f32_16x16x32_bf16 v[74:77], v[172:175], v[220:223], v[74:77]
	v_mfma_f32_16x16x32_bf16 v[126:129], v[168:171], v[200:203], v[126:129]
	v_mfma_f32_16x16x32_bf16 v[122:125], v[176:179], v[200:203], v[122:125]
	v_mfma_f32_16x16x32_bf16 v[110:113], v[168:171], v[208:211], v[110:113]
	v_mfma_f32_16x16x32_bf16 v[106:109], v[176:179], v[208:211], v[106:109]
	v_mfma_f32_16x16x32_bf16 v[94:97], v[168:171], v[216:219], v[94:97]
	v_mfma_f32_16x16x32_bf16 v[90:93], v[176:179], v[216:219], v[90:93]
	v_mfma_f32_16x16x32_bf16 v[78:81], v[168:171], v[224:227], v[78:81]
	v_mfma_f32_16x16x32_bf16 v[74:77], v[176:179], v[224:227], v[74:77]
	s_setprio 0
	s_setprio 1
	v_mfma_f32_16x16x32_bf16 v[118:121], v[180:183], v[196:199], v[118:121]
	v_mfma_f32_16x16x32_bf16 v[114:117], v[188:191], v[196:199], v[114:117]
	v_mfma_f32_16x16x32_bf16 v[102:105], v[180:183], v[204:207], v[102:105]
	v_mfma_f32_16x16x32_bf16 v[98:101], v[188:191], v[204:207], v[98:101]
	v_mfma_f32_16x16x32_bf16 v[86:89], v[180:183], v[212:215], v[86:89]
	v_mfma_f32_16x16x32_bf16 v[82:85], v[188:191], v[212:215], v[82:85]
	v_mfma_f32_16x16x32_bf16 v[70:73], v[180:183], v[220:223], v[70:73]
	v_mfma_f32_16x16x32_bf16 v[66:69], v[188:191], v[220:223], v[66:69]
	v_mfma_f32_16x16x32_bf16 v[118:121], v[184:187], v[200:203], v[118:121]
	v_mfma_f32_16x16x32_bf16 v[114:117], v[192:195], v[200:203], v[114:117]
	v_mfma_f32_16x16x32_bf16 v[102:105], v[184:187], v[208:211], v[102:105]
	v_mfma_f32_16x16x32_bf16 v[98:101], v[192:195], v[208:211], v[98:101]
	v_mfma_f32_16x16x32_bf16 v[86:89], v[184:187], v[216:219], v[86:89]
	v_mfma_f32_16x16x32_bf16 v[82:85], v[192:195], v[216:219], v[82:85]
	v_mfma_f32_16x16x32_bf16 v[70:73], v[184:187], v[224:227], v[70:73]
	v_mfma_f32_16x16x32_bf16 v[66:69], v[192:195], v[224:227], v[66:69]
	s_setprio 0
	s_barrier
	s_mov_b32 m0, s48
	s_add_u32 s64, s30, 0x2b0000
	global_load_lds_dwordx4 v132, s[30:31]
	s_mov_b32 m0, s49
	s_addc_u32 s65, s31, 0
	global_load_lds_dwordx4 v136, s[30:31]
	s_mov_b32 m0, s50
	ds_read_b128 v[196:199], v158 offset:16384
	global_load_lds_dwordx4 v132, s[64:65]
	s_mov_b32 m0, s51
	ds_read_b128 v[200:203], v158 offset:17408
	global_load_lds_dwordx4 v136, s[64:65]
	ds_read_b128 v[204:207], v158 offset:18432
	ds_read_b128 v[208:211], v158 offset:19456
	ds_read_b128 v[212:215], v158 offset:20480
	ds_read_b128 v[216:219], v158 offset:21504
	ds_read_b128 v[220:223], v158 offset:22528
	ds_read_b128 v[224:227], v158 offset:23552
	s_waitcnt vmcnt(6)
	s_waitcnt lgkmcnt(0)
	s_barrier
	s_setprio 1
	s_waitcnt lgkmcnt(0)
	v_mfma_f32_16x16x32_bf16 v[62:65], v[142:145], v[196:199], v[62:65]
	v_mfma_f32_16x16x32_bf16 v[58:61], v[172:175], v[196:199], v[58:61]
	v_mfma_f32_16x16x32_bf16 v[46:49], v[142:145], v[204:207], v[46:49]
	v_mfma_f32_16x16x32_bf16 v[42:45], v[172:175], v[204:207], v[42:45]
	v_mfma_f32_16x16x32_bf16 v[30:33], v[142:145], v[212:215], v[30:33]
	v_mfma_f32_16x16x32_bf16 v[26:29], v[172:175], v[212:215], v[26:29]
	v_mfma_f32_16x16x32_bf16 v[14:17], v[142:145], v[220:223], v[14:17]
	v_mfma_f32_16x16x32_bf16 v[10:13], v[172:175], v[220:223], v[10:13]
	v_mfma_f32_16x16x32_bf16 v[62:65], v[168:171], v[200:203], v[62:65]
	v_mfma_f32_16x16x32_bf16 v[58:61], v[176:179], v[200:203], v[58:61]
	v_mfma_f32_16x16x32_bf16 v[46:49], v[168:171], v[208:211], v[46:49]
	v_mfma_f32_16x16x32_bf16 v[42:45], v[176:179], v[208:211], v[42:45]
	v_mfma_f32_16x16x32_bf16 v[30:33], v[168:171], v[216:219], v[30:33]
	v_mfma_f32_16x16x32_bf16 v[26:29], v[176:179], v[216:219], v[26:29]
	v_mfma_f32_16x16x32_bf16 v[14:17], v[168:171], v[224:227], v[14:17]
	v_mfma_f32_16x16x32_bf16 v[10:13], v[176:179], v[224:227], v[10:13]
	s_setprio 0
	s_setprio 1
	v_mfma_f32_16x16x32_bf16 v[54:57], v[180:183], v[196:199], v[54:57]
	v_mfma_f32_16x16x32_bf16 v[50:53], v[188:191], v[196:199], v[50:53]
	v_mfma_f32_16x16x32_bf16 v[38:41], v[180:183], v[204:207], v[38:41]
	v_mfma_f32_16x16x32_bf16 v[34:37], v[188:191], v[204:207], v[34:37]
	v_mfma_f32_16x16x32_bf16 v[22:25], v[180:183], v[212:215], v[22:25]
	v_mfma_f32_16x16x32_bf16 v[18:21], v[188:191], v[212:215], v[18:21]
	v_mfma_f32_16x16x32_bf16 v[6:9], v[180:183], v[220:223], v[6:9]
	v_mfma_f32_16x16x32_bf16 v[2:5], v[188:191], v[220:223], v[2:5]
	v_mfma_f32_16x16x32_bf16 v[54:57], v[184:187], v[200:203], v[54:57]
	v_mfma_f32_16x16x32_bf16 v[50:53], v[192:195], v[200:203], v[50:53]
	v_mfma_f32_16x16x32_bf16 v[38:41], v[184:187], v[208:211], v[38:41]
	v_mfma_f32_16x16x32_bf16 v[34:37], v[192:195], v[208:211], v[34:37]
	v_mfma_f32_16x16x32_bf16 v[22:25], v[184:187], v[216:219], v[22:25]
	v_mfma_f32_16x16x32_bf16 v[18:21], v[192:195], v[216:219], v[18:21]
	v_mfma_f32_16x16x32_bf16 v[6:9], v[184:187], v[224:227], v[6:9]
	v_mfma_f32_16x16x32_bf16 v[2:5], v[192:195], v[224:227], v[2:5]
	s_setprio 0
	s_barrier
	s_mov_b32 m0, s39
	ds_read_b128 v[142:145], v159
	global_load_lds_dwordx4 v130, s[34:35]
	s_mov_b32 m0, s40
	ds_read_b128 v[168:171], v159 offset:1024
	global_load_lds_dwordx4 v134, s[34:35]
	s_add_u32 s34, s34, 0x2b0000
	s_addc_u32 s35, s35, 0
	s_mov_b32 m0, s41
	ds_read_b128 v[172:175], v159 offset:2048
	global_load_lds_dwordx4 v130, s[34:35]
	s_mov_b32 m0, s42
	ds_read_b128 v[176:179], v159 offset:3072
	global_load_lds_dwordx4 v134, s[34:35]
	ds_read_b128 v[180:183], v160
	ds_read_b128 v[184:187], v160 offset:1024
	ds_read_b128 v[188:191], v160 offset:2048
	ds_read_b128 v[192:195], v160 offset:3072
	ds_read_b128 v[196:199], v158 offset:32768
	ds_read_b128 v[200:203], v158 offset:33792
	ds_read_b128 v[204:207], v158 offset:34816
	ds_read_b128 v[208:211], v158 offset:35840
	ds_read_b128 v[212:215], v158 offset:36864
	ds_read_b128 v[216:219], v158 offset:37888
	ds_read_b128 v[220:223], v158 offset:38912
	ds_read_b128 v[224:227], v158 offset:39936
	s_waitcnt vmcnt(8)
	s_waitcnt lgkmcnt(0)
	s_barrier
	s_setprio 1
	s_waitcnt lgkmcnt(0)
	v_mfma_f32_16x16x32_bf16 v[126:129], v[142:145], v[196:199], v[126:129]
	v_mfma_f32_16x16x32_bf16 v[122:125], v[172:175], v[196:199], v[122:125]
	v_mfma_f32_16x16x32_bf16 v[110:113], v[142:145], v[204:207], v[110:113]
	v_mfma_f32_16x16x32_bf16 v[106:109], v[172:175], v[204:207], v[106:109]
	v_mfma_f32_16x16x32_bf16 v[94:97], v[142:145], v[212:215], v[94:97]
	v_mfma_f32_16x16x32_bf16 v[90:93], v[172:175], v[212:215], v[90:93]
	v_mfma_f32_16x16x32_bf16 v[78:81], v[142:145], v[220:223], v[78:81]
	v_mfma_f32_16x16x32_bf16 v[74:77], v[172:175], v[220:223], v[74:77]
	v_mfma_f32_16x16x32_bf16 v[126:129], v[168:171], v[200:203], v[126:129]
	v_mfma_f32_16x16x32_bf16 v[122:125], v[176:179], v[200:203], v[122:125]
	v_mfma_f32_16x16x32_bf16 v[110:113], v[168:171], v[208:211], v[110:113]
	v_mfma_f32_16x16x32_bf16 v[106:109], v[176:179], v[208:211], v[106:109]
	v_mfma_f32_16x16x32_bf16 v[94:97], v[168:171], v[216:219], v[94:97]
	v_mfma_f32_16x16x32_bf16 v[90:93], v[176:179], v[216:219], v[90:93]
	v_mfma_f32_16x16x32_bf16 v[78:81], v[168:171], v[224:227], v[78:81]
	v_mfma_f32_16x16x32_bf16 v[74:77], v[176:179], v[224:227], v[74:77]
	s_setprio 0
	s_setprio 1
	v_mfma_f32_16x16x32_bf16 v[118:121], v[180:183], v[196:199], v[118:121]
	v_mfma_f32_16x16x32_bf16 v[114:117], v[188:191], v[196:199], v[114:117]
	v_mfma_f32_16x16x32_bf16 v[102:105], v[180:183], v[204:207], v[102:105]
	v_mfma_f32_16x16x32_bf16 v[98:101], v[188:191], v[204:207], v[98:101]
	v_mfma_f32_16x16x32_bf16 v[86:89], v[180:183], v[212:215], v[86:89]
	v_mfma_f32_16x16x32_bf16 v[82:85], v[188:191], v[212:215], v[82:85]
	v_mfma_f32_16x16x32_bf16 v[70:73], v[180:183], v[220:223], v[70:73]
	v_mfma_f32_16x16x32_bf16 v[66:69], v[188:191], v[220:223], v[66:69]
	v_mfma_f32_16x16x32_bf16 v[118:121], v[184:187], v[200:203], v[118:121]
	v_mfma_f32_16x16x32_bf16 v[114:117], v[192:195], v[200:203], v[114:117]
	v_mfma_f32_16x16x32_bf16 v[102:105], v[184:187], v[208:211], v[102:105]
	v_mfma_f32_16x16x32_bf16 v[98:101], v[192:195], v[208:211], v[98:101]
	v_mfma_f32_16x16x32_bf16 v[86:89], v[184:187], v[216:219], v[86:89]
	v_mfma_f32_16x16x32_bf16 v[82:85], v[192:195], v[216:219], v[82:85]
	v_mfma_f32_16x16x32_bf16 v[70:73], v[184:187], v[224:227], v[70:73]
	v_mfma_f32_16x16x32_bf16 v[66:69], v[192:195], v[224:227], v[66:69]
	s_setprio 0
	s_barrier
	s_mov_b32 m0, s52
	s_add_u32 s30, s30, 0x80
	s_addc_u32 s31, s31, 0
	global_load_lds_dwordx4 v132, s[30:31]
	s_mov_b32 m0, s53
	ds_read_b128 v[196:199], v158 offset:49152
	global_load_lds_dwordx4 v136, s[30:31]
	s_mov_b32 m0, s54
	s_add_u32 s30, s30, 0x2b0000
	s_addc_u32 s31, s31, 0
	global_load_lds_dwordx4 v132, s[30:31]
	s_mov_b32 m0, s55
	ds_read_b128 v[200:203], v158 offset:50176
	global_load_lds_dwordx4 v136, s[30:31]
	ds_read_b128 v[204:207], v158 offset:51200
	ds_read_b128 v[208:211], v158 offset:52224
	ds_read_b128 v[212:215], v158 offset:53248
	ds_read_b128 v[216:219], v158 offset:54272
	ds_read_b128 v[220:223], v158 offset:55296
	ds_read_b128 v[224:227], v158 offset:56320
	s_waitcnt vmcnt(6)
	s_waitcnt lgkmcnt(0)
	s_barrier
	s_setprio 1
	s_waitcnt lgkmcnt(0)
	v_mfma_f32_16x16x32_bf16 v[62:65], v[142:145], v[196:199], v[62:65]
	v_mfma_f32_16x16x32_bf16 v[58:61], v[172:175], v[196:199], v[58:61]
	v_mfma_f32_16x16x32_bf16 v[46:49], v[142:145], v[204:207], v[46:49]
	v_mfma_f32_16x16x32_bf16 v[42:45], v[172:175], v[204:207], v[42:45]
	v_mfma_f32_16x16x32_bf16 v[30:33], v[142:145], v[212:215], v[30:33]
	v_mfma_f32_16x16x32_bf16 v[26:29], v[172:175], v[212:215], v[26:29]
	v_mfma_f32_16x16x32_bf16 v[14:17], v[142:145], v[220:223], v[14:17]
	v_mfma_f32_16x16x32_bf16 v[10:13], v[172:175], v[220:223], v[10:13]
	v_mfma_f32_16x16x32_bf16 v[62:65], v[168:171], v[200:203], v[62:65]
	v_mfma_f32_16x16x32_bf16 v[58:61], v[176:179], v[200:203], v[58:61]
	v_mfma_f32_16x16x32_bf16 v[46:49], v[168:171], v[208:211], v[46:49]
	v_mfma_f32_16x16x32_bf16 v[42:45], v[176:179], v[208:211], v[42:45]
	v_mfma_f32_16x16x32_bf16 v[30:33], v[168:171], v[216:219], v[30:33]
	v_mfma_f32_16x16x32_bf16 v[26:29], v[176:179], v[216:219], v[26:29]
	v_mfma_f32_16x16x32_bf16 v[14:17], v[168:171], v[224:227], v[14:17]
	v_mfma_f32_16x16x32_bf16 v[10:13], v[176:179], v[224:227], v[10:13]
	s_setprio 0
	s_setprio 1
	v_mfma_f32_16x16x32_bf16 v[54:57], v[180:183], v[196:199], v[54:57]
	v_mfma_f32_16x16x32_bf16 v[50:53], v[188:191], v[196:199], v[50:53]
	v_mfma_f32_16x16x32_bf16 v[38:41], v[180:183], v[204:207], v[38:41]
	v_mfma_f32_16x16x32_bf16 v[34:37], v[188:191], v[204:207], v[34:37]
	v_mfma_f32_16x16x32_bf16 v[22:25], v[180:183], v[212:215], v[22:25]
	v_mfma_f32_16x16x32_bf16 v[18:21], v[188:191], v[212:215], v[18:21]
	v_mfma_f32_16x16x32_bf16 v[6:9], v[180:183], v[220:223], v[6:9]
	v_mfma_f32_16x16x32_bf16 v[2:5], v[188:191], v[220:223], v[2:5]
	v_mfma_f32_16x16x32_bf16 v[54:57], v[184:187], v[200:203], v[54:57]
	v_mfma_f32_16x16x32_bf16 v[50:53], v[192:195], v[200:203], v[50:53]
	v_mfma_f32_16x16x32_bf16 v[38:41], v[184:187], v[208:211], v[38:41]
	v_mfma_f32_16x16x32_bf16 v[34:37], v[192:195], v[208:211], v[34:37]
	v_mfma_f32_16x16x32_bf16 v[22:25], v[184:187], v[216:219], v[22:25]
	v_mfma_f32_16x16x32_bf16 v[18:21], v[192:195], v[216:219], v[18:21]
	v_mfma_f32_16x16x32_bf16 v[6:9], v[184:187], v[224:227], v[6:9]
	v_mfma_f32_16x16x32_bf16 v[2:5], v[192:195], v[224:227], v[2:5]
	s_setprio 0
	s_barrier
	s_add_i32 s62, s62, 2
	s_add_u32 s28, s28, 0x100
	s_addc_u32 s29, s29, 0
	s_add_u32 s60, s60, 0x100
	s_addc_u32 s61, s61, 0
	s_cmpk_gt_u32 s62, 0xa9
	s_cbranch_scc0 .LBB0_2618
	s_and_b64 vcc, exec, s[12:13]
	s_cbranch_vccz .LBB0_2621
	s_barrier
